# GEMM K-loops: load segments (ds_read + LDS-DMA issue) run at s_setprio 2, above the partner half's MFMA segment at 1
# baseline (speedup 1.0000x reference)
.LBB0_226:
	s_add_i32 vcc_lo, s82, 2
	s_add_u32 s20, s66, 0xffff0080
	s_addc_u32 s21, s67, -1
	s_add_i32 s52, 0, 0x10000
	s_cmp_eq_u32 s60, s82
	s_cselect_b32 s87, s39, s21
	s_cselect_b32 s86, s41, s20
	s_cselect_b32 s83, s88, s95
	s_cselect_b32 s82, s89, s94
	s_add_i32 s53, 0, 0x14000
	v_add_u32_e32 v154, s52, v140
	v_add_u32_e32 v170, s53, v140
	ds_read_b128 v[142:145], v154
	ds_read_b128 v[146:149], v154 offset:1024
	ds_read_b128 v[150:153], v154 offset:2048
	ds_read_b128 v[154:157], v154 offset:3072
	ds_read_b128 v[158:161], v170
	ds_read_b128 v[162:165], v170 offset:1024
	ds_read_b128 v[166:169], v170 offset:2048
	ds_read_b128 v[170:173], v170 offset:3072
	v_lshl_add_u64 v[186:187], s[66:67], 0, v[134:135]
	s_add_i32 m0, s13, 0xc000
	ds_read_b128 v[174:177], v141
	ds_read_b128 v[178:181], v141 offset:1024
	ds_read_b128 v[182:185], v141 offset:2048
	ds_read_b128 v[202:205], v141 offset:3072
	ds_read_b128 v[216:219], v141 offset:4096
	ds_read_b128 v[220:223], v141 offset:5120
	ds_read_b128 v[224:227], v141 offset:6144
	ds_read_b128 v[228:231], v141 offset:7168
	global_load_lds_dwordx4 v[186:187], off
	v_lshl_add_u64 v[186:187], s[66:67], 0, v[136:137]
	s_add_i32 m0, s13, 0xe000
	s_nop 0
	global_load_lds_dwordx4 v[186:187], off
	s_waitcnt vmcnt(8)
	s_waitcnt lgkmcnt(0)
	s_barrier
	s_setprio 1
	s_waitcnt lgkmcnt(0)
	v_mfma_f32_16x16x32_bf16 v[120:123], v[142:145], v[174:177], v[120:123]
	v_mfma_f32_16x16x32_bf16 v[124:127], v[150:153], v[174:177], v[124:127]
	v_mfma_f32_16x16x32_bf16 v[108:111], v[142:145], v[182:185], v[108:111]
	v_mfma_f32_16x16x32_bf16 v[104:107], v[150:153], v[182:185], v[104:107]
	v_mfma_f32_16x16x32_bf16 v[92:95], v[142:145], v[216:219], v[92:95]
	v_mfma_f32_16x16x32_bf16 v[88:91], v[150:153], v[216:219], v[88:91]
	v_mfma_f32_16x16x32_bf16 v[76:79], v[142:145], v[224:227], v[76:79]
	v_mfma_f32_16x16x32_bf16 v[72:75], v[150:153], v[224:227], v[72:75]
	v_mfma_f32_16x16x32_bf16 v[120:123], v[146:149], v[178:181], v[120:123]
	v_mfma_f32_16x16x32_bf16 v[124:127], v[154:157], v[178:181], v[124:127]
	v_mfma_f32_16x16x32_bf16 v[108:111], v[146:149], v[202:205], v[108:111]
	v_mfma_f32_16x16x32_bf16 v[104:107], v[154:157], v[202:205], v[104:107]
	v_mfma_f32_16x16x32_bf16 v[92:95], v[146:149], v[220:223], v[92:95]
	v_mfma_f32_16x16x32_bf16 v[88:91], v[154:157], v[220:223], v[88:91]
	v_mfma_f32_16x16x32_bf16 v[76:79], v[146:149], v[228:231], v[76:79]
	v_mfma_f32_16x16x32_bf16 v[72:75], v[154:157], v[228:231], v[72:75]
	s_setprio 0
	s_setprio 1
	v_mfma_f32_16x16x32_bf16 v[116:119], v[158:161], v[174:177], v[116:119]
	v_mfma_f32_16x16x32_bf16 v[112:115], v[166:169], v[174:177], v[112:115]
	v_mfma_f32_16x16x32_bf16 v[100:103], v[158:161], v[182:185], v[100:103]
	v_mfma_f32_16x16x32_bf16 v[96:99], v[166:169], v[182:185], v[96:99]
	v_mfma_f32_16x16x32_bf16 v[84:87], v[158:161], v[216:219], v[84:87]
	v_mfma_f32_16x16x32_bf16 v[80:83], v[166:169], v[216:219], v[80:83]
	v_mfma_f32_16x16x32_bf16 v[68:71], v[158:161], v[224:227], v[68:71]
	v_mfma_f32_16x16x32_bf16 v[64:67], v[166:169], v[224:227], v[64:67]
	v_mfma_f32_16x16x32_bf16 v[116:119], v[162:165], v[178:181], v[116:119]
	v_mfma_f32_16x16x32_bf16 v[112:115], v[170:173], v[178:181], v[112:115]
	v_mfma_f32_16x16x32_bf16 v[100:103], v[162:165], v[202:205], v[100:103]
	v_mfma_f32_16x16x32_bf16 v[96:99], v[170:173], v[202:205], v[96:99]
	v_mfma_f32_16x16x32_bf16 v[84:87], v[162:165], v[220:223], v[84:87]
	v_mfma_f32_16x16x32_bf16 v[80:83], v[170:173], v[220:223], v[80:83]
	v_mfma_f32_16x16x32_bf16 v[68:71], v[162:165], v[228:231], v[68:71]
	v_mfma_f32_16x16x32_bf16 v[64:67], v[170:173], v[228:231], v[64:67]
	s_setprio 0
	s_barrier
	s_setprio 2
	s_add_i32 s20, s52, s12
	v_lshl_add_u64 v[186:187], s[82:83], 0, v[188:189]
	s_mov_b32 m0, s20
	ds_read_b128 v[174:177], v141 offset:16384
	ds_read_b128 v[178:181], v141 offset:17408
	ds_read_b128 v[182:185], v141 offset:18432
	ds_read_b128 v[202:205], v141 offset:19456
	ds_read_b128 v[216:219], v141 offset:20480
	ds_read_b128 v[220:223], v141 offset:21504
	ds_read_b128 v[224:227], v141 offset:22528
	ds_read_b128 v[228:231], v141 offset:23552
	global_load_lds_dwordx4 v[186:187], off
	s_add_i32 m0, s20, 0x2000
	s_add_u32 s20, s82, 0x10000
	v_lshl_add_u64 v[194:195], s[82:83], 0, v[128:129]
	s_addc_u32 s21, s83, 0
	s_add_i32 s52, s53, s12
	global_load_lds_dwordx4 v[194:195], off
	v_lshl_add_u64 v[196:197], s[20:21], 0, v[188:189]
	s_mov_b32 m0, s52
	v_lshl_add_u64 v[232:233], s[86:87], 0, v[130:131]
	global_load_lds_dwordx4 v[196:197], off
	v_lshl_add_u64 v[196:197], s[20:21], 0, v[128:129]
	s_add_i32 m0, s52, 0x2000
	s_nop 0
	global_load_lds_dwordx4 v[196:197], off
	v_lshl_add_u64 v[196:197], s[86:87], 0, v[132:133]
	s_mov_b32 m0, s13
	s_nop 0
	global_load_lds_dwordx4 v[196:197], off
	s_mov_b32 m0, s28
	s_nop 0
	global_load_lds_dwordx4 v[232:233], off
	s_waitcnt vmcnt(8)
	s_waitcnt lgkmcnt(0)
	s_barrier
	s_setprio 1
	s_waitcnt lgkmcnt(0)
	v_mfma_f32_16x16x32_bf16 v[60:63], v[142:145], v[174:177], v[60:63]
	v_mfma_f32_16x16x32_bf16 v[56:59], v[150:153], v[174:177], v[56:59]
	v_mfma_f32_16x16x32_bf16 v[44:47], v[142:145], v[182:185], v[44:47]
	v_mfma_f32_16x16x32_bf16 v[40:43], v[150:153], v[182:185], v[40:43]
	v_mfma_f32_16x16x32_bf16 v[28:31], v[142:145], v[216:219], v[28:31]
	v_mfma_f32_16x16x32_bf16 v[24:27], v[150:153], v[216:219], v[24:27]
	v_mfma_f32_16x16x32_bf16 v[12:15], v[142:145], v[224:227], v[12:15]
	v_mfma_f32_16x16x32_bf16 v[8:11], v[150:153], v[224:227], v[8:11]
	v_mfma_f32_16x16x32_bf16 v[60:63], v[146:149], v[178:181], v[60:63]
	v_mfma_f32_16x16x32_bf16 v[56:59], v[154:157], v[178:181], v[56:59]
	v_mfma_f32_16x16x32_bf16 v[44:47], v[146:149], v[202:205], v[44:47]
	v_mfma_f32_16x16x32_bf16 v[40:43], v[154:157], v[202:205], v[40:43]
	v_mfma_f32_16x16x32_bf16 v[28:31], v[146:149], v[220:223], v[28:31]
	v_mfma_f32_16x16x32_bf16 v[24:27], v[154:157], v[220:223], v[24:27]
	v_mfma_f32_16x16x32_bf16 v[12:15], v[146:149], v[228:231], v[12:15]
	v_mfma_f32_16x16x32_bf16 v[8:11], v[154:157], v[228:231], v[8:11]
	s_setprio 0
	s_setprio 1
	v_mfma_f32_16x16x32_bf16 v[52:55], v[158:161], v[174:177], v[52:55]
	v_mfma_f32_16x16x32_bf16 v[48:51], v[166:169], v[174:177], v[48:51]
	v_mfma_f32_16x16x32_bf16 v[36:39], v[158:161], v[182:185], v[36:39]
	v_mfma_f32_16x16x32_bf16 v[32:35], v[166:169], v[182:185], v[32:35]
	v_mfma_f32_16x16x32_bf16 v[20:23], v[158:161], v[216:219], v[20:23]
	v_mfma_f32_16x16x32_bf16 v[16:19], v[166:169], v[216:219], v[16:19]
	v_mfma_f32_16x16x32_bf16 v[4:7], v[158:161], v[224:227], v[4:7]
	v_mfma_f32_16x16x32_bf16 v[0:3], v[166:169], v[224:227], v[0:3]
	v_mfma_f32_16x16x32_bf16 v[52:55], v[162:165], v[178:181], v[52:55]
	v_mfma_f32_16x16x32_bf16 v[48:51], v[170:173], v[178:181], v[48:51]
	v_mfma_f32_16x16x32_bf16 v[36:39], v[162:165], v[202:205], v[36:39]
	v_mfma_f32_16x16x32_bf16 v[32:35], v[170:173], v[202:205], v[32:35]
	v_mfma_f32_16x16x32_bf16 v[20:23], v[162:165], v[220:223], v[20:23]
	v_mfma_f32_16x16x32_bf16 v[16:19], v[170:173], v[220:223], v[16:19]
	v_mfma_f32_16x16x32_bf16 v[4:7], v[162:165], v[228:231], v[4:7]
	v_mfma_f32_16x16x32_bf16 v[0:3], v[170:173], v[228:231], v[0:3]
	s_setprio 0
	s_barrier
	s_setprio 2
	s_add_i32 s52, 0, 0x18000
	s_add_i32 s53, 0, 0x1c000
	v_add_u32_e32 v154, s52, v140
	v_add_u32_e32 v170, s53, v140
	ds_read_b128 v[142:145], v154
	ds_read_b128 v[146:149], v154 offset:1024
	ds_read_b128 v[150:153], v154 offset:2048
	ds_read_b128 v[154:157], v154 offset:3072
	ds_read_b128 v[158:161], v170
	ds_read_b128 v[162:165], v170 offset:1024
	ds_read_b128 v[166:169], v170 offset:2048
	ds_read_b128 v[170:173], v170 offset:3072
	s_add_u32 s20, s86, 0x10000
	s_addc_u32 s21, s87, 0
	s_mov_b32 m0, s46
	v_lshl_add_u64 v[234:235], s[20:21], 0, v[132:133]
	ds_read_b128 v[174:177], v141 offset:32768
	ds_read_b128 v[178:181], v141 offset:33792
	ds_read_b128 v[182:185], v141 offset:34816
	ds_read_b128 v[202:205], v141 offset:35840
	ds_read_b128 v[216:219], v141 offset:36864
	ds_read_b128 v[220:223], v141 offset:37888
	ds_read_b128 v[224:227], v141 offset:38912
	ds_read_b128 v[228:231], v141 offset:39936
	global_load_lds_dwordx4 v[234:235], off
	v_lshl_add_u64 v[234:235], s[20:21], 0, v[130:131]
	s_mov_b32 m0, s47
	s_nop 0
	global_load_lds_dwordx4 v[234:235], off
	s_waitcnt vmcnt(8)
	s_waitcnt lgkmcnt(0)
	s_barrier
	s_setprio 1
	s_waitcnt lgkmcnt(0)
	v_mfma_f32_16x16x32_bf16 v[120:123], v[142:145], v[174:177], v[120:123]
	v_mfma_f32_16x16x32_bf16 v[124:127], v[150:153], v[174:177], v[124:127]
	v_mfma_f32_16x16x32_bf16 v[108:111], v[142:145], v[182:185], v[108:111]
	v_mfma_f32_16x16x32_bf16 v[104:107], v[150:153], v[182:185], v[104:107]
	v_mfma_f32_16x16x32_bf16 v[92:95], v[142:145], v[216:219], v[92:95]
	v_mfma_f32_16x16x32_bf16 v[88:91], v[150:153], v[216:219], v[88:91]
	v_mfma_f32_16x16x32_bf16 v[76:79], v[142:145], v[224:227], v[76:79]
	v_mfma_f32_16x16x32_bf16 v[72:75], v[150:153], v[224:227], v[72:75]
	v_mfma_f32_16x16x32_bf16 v[120:123], v[146:149], v[178:181], v[120:123]
	v_mfma_f32_16x16x32_bf16 v[124:127], v[154:157], v[178:181], v[124:127]
	v_mfma_f32_16x16x32_bf16 v[108:111], v[146:149], v[202:205], v[108:111]
	v_mfma_f32_16x16x32_bf16 v[104:107], v[154:157], v[202:205], v[104:107]
	v_mfma_f32_16x16x32_bf16 v[92:95], v[146:149], v[220:223], v[92:95]
	v_mfma_f32_16x16x32_bf16 v[88:91], v[154:157], v[220:223], v[88:91]
	v_mfma_f32_16x16x32_bf16 v[76:79], v[146:149], v[228:231], v[76:79]
	v_mfma_f32_16x16x32_bf16 v[72:75], v[154:157], v[228:231], v[72:75]
	s_setprio 0
	s_setprio 1
	v_mfma_f32_16x16x32_bf16 v[116:119], v[158:161], v[174:177], v[116:119]
	v_mfma_f32_16x16x32_bf16 v[112:115], v[166:169], v[174:177], v[112:115]
	v_mfma_f32_16x16x32_bf16 v[100:103], v[158:161], v[182:185], v[100:103]
	v_mfma_f32_16x16x32_bf16 v[96:99], v[166:169], v[182:185], v[96:99]
	v_mfma_f32_16x16x32_bf16 v[84:87], v[158:161], v[216:219], v[84:87]
	v_mfma_f32_16x16x32_bf16 v[80:83], v[166:169], v[216:219], v[80:83]
	v_mfma_f32_16x16x32_bf16 v[68:71], v[158:161], v[224:227], v[68:71]
	v_mfma_f32_16x16x32_bf16 v[64:67], v[166:169], v[224:227], v[64:67]
	v_mfma_f32_16x16x32_bf16 v[116:119], v[162:165], v[178:181], v[116:119]
	v_mfma_f32_16x16x32_bf16 v[112:115], v[170:173], v[178:181], v[112:115]
	v_mfma_f32_16x16x32_bf16 v[100:103], v[162:165], v[202:205], v[100:103]
	v_mfma_f32_16x16x32_bf16 v[96:99], v[170:173], v[202:205], v[96:99]
	v_mfma_f32_16x16x32_bf16 v[84:87], v[162:165], v[220:223], v[84:87]
	v_mfma_f32_16x16x32_bf16 v[80:83], v[170:173], v[220:223], v[80:83]
	v_mfma_f32_16x16x32_bf16 v[68:71], v[162:165], v[228:231], v[68:71]
	v_mfma_f32_16x16x32_bf16 v[64:67], v[170:173], v[228:231], v[64:67]
	s_setprio 0
	s_barrier
	s_setprio 2
	s_add_i32 s20, s52, s12
	v_lshl_add_u64 v[186:187], v[186:187], 0, s[62:63]
	s_mov_b32 m0, s20
	ds_read_b128 v[174:177], v141 offset:49152
	ds_read_b128 v[178:181], v141 offset:50176
	ds_read_b128 v[182:185], v141 offset:51200
	ds_read_b128 v[202:205], v141 offset:52224
	ds_read_b128 v[216:219], v141 offset:53248
	ds_read_b128 v[220:223], v141 offset:54272
	ds_read_b128 v[224:227], v141 offset:55296
	ds_read_b128 v[228:231], v141 offset:56320
	global_load_lds_dwordx4 v[186:187], off
	s_add_i32 m0, s20, 0x2000
	s_add_u32 s20, s82, 0x10080
	v_lshl_add_u64 v[186:187], v[194:195], 0, s[62:63]
	s_addc_u32 s21, s83, 0
	s_add_i32 s52, s53, s12
	global_load_lds_dwordx4 v[186:187], off
	v_lshl_add_u64 v[186:187], s[20:21], 0, v[188:189]
	s_mov_b32 m0, s52
	s_nop 0
	global_load_lds_dwordx4 v[186:187], off
	v_lshl_add_u64 v[186:187], s[20:21], 0, v[128:129]
	s_add_i32 m0, s52, 0x2000
	s_nop 0
	global_load_lds_dwordx4 v[186:187], off
	v_lshl_add_u64 v[186:187], v[196:197], 0, s[62:63]
	s_mov_b32 m0, s56
	s_nop 0
	global_load_lds_dwordx4 v[186:187], off
	v_lshl_add_u64 v[186:187], v[232:233], 0, s[62:63]
	s_mov_b32 m0, s57
	s_nop 0
	global_load_lds_dwordx4 v[186:187], off
	s_waitcnt vmcnt(8)
	s_waitcnt lgkmcnt(0)
	s_barrier
	s_setprio 1
	s_waitcnt lgkmcnt(0)
	v_mfma_f32_16x16x32_bf16 v[60:63], v[142:145], v[174:177], v[60:63]
	v_mfma_f32_16x16x32_bf16 v[56:59], v[150:153], v[174:177], v[56:59]
	v_mfma_f32_16x16x32_bf16 v[44:47], v[142:145], v[182:185], v[44:47]
	v_mfma_f32_16x16x32_bf16 v[40:43], v[150:153], v[182:185], v[40:43]
	v_mfma_f32_16x16x32_bf16 v[28:31], v[142:145], v[216:219], v[28:31]
	v_mfma_f32_16x16x32_bf16 v[24:27], v[150:153], v[216:219], v[24:27]
	v_mfma_f32_16x16x32_bf16 v[12:15], v[142:145], v[224:227], v[12:15]
	v_mfma_f32_16x16x32_bf16 v[8:11], v[150:153], v[224:227], v[8:11]
	v_mfma_f32_16x16x32_bf16 v[60:63], v[146:149], v[178:181], v[60:63]
	v_mfma_f32_16x16x32_bf16 v[56:59], v[154:157], v[178:181], v[56:59]
	v_mfma_f32_16x16x32_bf16 v[44:47], v[146:149], v[202:205], v[44:47]
	v_mfma_f32_16x16x32_bf16 v[40:43], v[154:157], v[202:205], v[40:43]
	v_mfma_f32_16x16x32_bf16 v[28:31], v[146:149], v[220:223], v[28:31]
	v_mfma_f32_16x16x32_bf16 v[24:27], v[154:157], v[220:223], v[24:27]
	v_mfma_f32_16x16x32_bf16 v[12:15], v[146:149], v[228:231], v[12:15]
	v_mfma_f32_16x16x32_bf16 v[8:11], v[154:157], v[228:231], v[8:11]
	s_setprio 0
	s_setprio 1
	v_mfma_f32_16x16x32_bf16 v[52:55], v[158:161], v[174:177], v[52:55]
	v_mfma_f32_16x16x32_bf16 v[48:51], v[166:169], v[174:177], v[48:51]
	v_mfma_f32_16x16x32_bf16 v[36:39], v[158:161], v[182:185], v[36:39]
	v_mfma_f32_16x16x32_bf16 v[32:35], v[166:169], v[182:185], v[32:35]
	v_mfma_f32_16x16x32_bf16 v[20:23], v[158:161], v[216:219], v[20:23]
	v_mfma_f32_16x16x32_bf16 v[16:19], v[166:169], v[216:219], v[16:19]
	v_mfma_f32_16x16x32_bf16 v[4:7], v[158:161], v[224:227], v[4:7]
	v_mfma_f32_16x16x32_bf16 v[0:3], v[166:169], v[224:227], v[0:3]
	v_mfma_f32_16x16x32_bf16 v[52:55], v[162:165], v[178:181], v[52:55]
	v_mfma_f32_16x16x32_bf16 v[48:51], v[170:173], v[178:181], v[48:51]
	v_mfma_f32_16x16x32_bf16 v[36:39], v[162:165], v[202:205], v[36:39]
	v_mfma_f32_16x16x32_bf16 v[32:35], v[170:173], v[202:205], v[32:35]
	v_mfma_f32_16x16x32_bf16 v[20:23], v[162:165], v[220:223], v[20:23]
	v_mfma_f32_16x16x32_bf16 v[16:19], v[170:173], v[220:223], v[16:19]
	v_mfma_f32_16x16x32_bf16 v[4:7], v[162:165], v[228:231], v[4:7]
	v_mfma_f32_16x16x32_bf16 v[0:3], v[170:173], v[228:231], v[0:3]
	s_setprio 0
	s_barrier
	s_setprio 2
	s_add_u32 s66, s66, 0x100
	s_addc_u32 s67, s67, 0
	s_add_u32 s94, s94, 0x100
	s_addc_u32 s95, s95, 0
	s_cmp_ge_i32 vcc_lo, s48
	s_mov_b32 s82, vcc_lo
	s_cbranch_scc0 .LBB0_226
	s_setprio 0
	s_mov_b64 s[88:89], 0x8000

.LBB0_247:
	s_add_i32 s61, s40, 2
	s_add_u32 s20, s38, 0xfffc0080
	s_addc_u32 s21, s39, -1
	s_add_i32 s52, 0, 0x10000
	s_cmp_eq_u32 s49, s40
	s_cselect_b32 s59, s35, s21
	s_cselect_b32 s58, s67, s20
	s_cselect_b32 s41, vcc_lo, s83
	s_cselect_b32 s40, vcc_hi, s82
	s_add_i32 s53, 0, 0x14000
	v_add_u32_e32 v148, s52, v168
	v_add_u32_e32 v164, s53, v168
	ds_read_b128 v[128:131], v148
	ds_read_b128 v[140:143], v148 offset:1024
	ds_read_b128 v[144:147], v148 offset:2048
	ds_read_b128 v[148:151], v148 offset:3072
	ds_read_b128 v[152:155], v164
	ds_read_b128 v[156:159], v164 offset:1024
	ds_read_b128 v[160:163], v164 offset:2048
	ds_read_b128 v[170:173], v164 offset:3072
	v_lshl_add_u64 v[164:165], s[38:39], 0, v[136:137]
	s_add_i32 m0, s46, 0xc000
	ds_read_b128 v[174:177], v169
	ds_read_b128 v[178:181], v169 offset:1024
	ds_read_b128 v[182:185], v169 offset:2048
	ds_read_b128 v[202:205], v169 offset:3072
	ds_read_b128 v[216:219], v169 offset:4096
	ds_read_b128 v[220:223], v169 offset:5120
	ds_read_b128 v[224:227], v169 offset:6144
	ds_read_b128 v[228:231], v169 offset:7168
	global_load_lds_dwordx4 v[164:165], off
	v_lshl_add_u64 v[164:165], s[38:39], 0, v[138:139]
	s_add_i32 m0, s46, 0xe000
	s_nop 0
	global_load_lds_dwordx4 v[164:165], off
	s_waitcnt vmcnt(8)
	s_waitcnt lgkmcnt(0)
	s_barrier
	s_setprio 1
	s_waitcnt lgkmcnt(0)
	v_mfma_f32_16x16x32_bf16 v[120:123], v[128:131], v[174:177], v[120:123]
	v_mfma_f32_16x16x32_bf16 v[124:127], v[144:147], v[174:177], v[124:127]
	v_mfma_f32_16x16x32_bf16 v[108:111], v[128:131], v[182:185], v[108:111]
	v_mfma_f32_16x16x32_bf16 v[104:107], v[144:147], v[182:185], v[104:107]
	v_mfma_f32_16x16x32_bf16 v[92:95], v[128:131], v[216:219], v[92:95]
	v_mfma_f32_16x16x32_bf16 v[88:91], v[144:147], v[216:219], v[88:91]
	v_mfma_f32_16x16x32_bf16 v[76:79], v[128:131], v[224:227], v[76:79]
	v_mfma_f32_16x16x32_bf16 v[72:75], v[144:147], v[224:227], v[72:75]
	v_mfma_f32_16x16x32_bf16 v[120:123], v[140:143], v[178:181], v[120:123]
	v_mfma_f32_16x16x32_bf16 v[124:127], v[148:151], v[178:181], v[124:127]
	v_mfma_f32_16x16x32_bf16 v[108:111], v[140:143], v[202:205], v[108:111]
	v_mfma_f32_16x16x32_bf16 v[104:107], v[148:151], v[202:205], v[104:107]
	v_mfma_f32_16x16x32_bf16 v[92:95], v[140:143], v[220:223], v[92:95]
	v_mfma_f32_16x16x32_bf16 v[88:91], v[148:151], v[220:223], v[88:91]
	v_mfma_f32_16x16x32_bf16 v[76:79], v[140:143], v[228:231], v[76:79]
	v_mfma_f32_16x16x32_bf16 v[72:75], v[148:151], v[228:231], v[72:75]
	s_setprio 0
	s_setprio 1
	v_mfma_f32_16x16x32_bf16 v[116:119], v[152:155], v[174:177], v[116:119]
	v_mfma_f32_16x16x32_bf16 v[112:115], v[160:163], v[174:177], v[112:115]
	v_mfma_f32_16x16x32_bf16 v[100:103], v[152:155], v[182:185], v[100:103]
	v_mfma_f32_16x16x32_bf16 v[96:99], v[160:163], v[182:185], v[96:99]
	v_mfma_f32_16x16x32_bf16 v[84:87], v[152:155], v[216:219], v[84:87]
	v_mfma_f32_16x16x32_bf16 v[80:83], v[160:163], v[216:219], v[80:83]
	v_mfma_f32_16x16x32_bf16 v[68:71], v[152:155], v[224:227], v[68:71]
	v_mfma_f32_16x16x32_bf16 v[64:67], v[160:163], v[224:227], v[64:67]
	v_mfma_f32_16x16x32_bf16 v[116:119], v[156:159], v[178:181], v[116:119]
	v_mfma_f32_16x16x32_bf16 v[112:115], v[170:173], v[178:181], v[112:115]
	v_mfma_f32_16x16x32_bf16 v[100:103], v[156:159], v[202:205], v[100:103]
	v_mfma_f32_16x16x32_bf16 v[96:99], v[170:173], v[202:205], v[96:99]
	v_mfma_f32_16x16x32_bf16 v[84:87], v[156:159], v[220:223], v[84:87]
	v_mfma_f32_16x16x32_bf16 v[80:83], v[170:173], v[220:223], v[80:83]
	v_mfma_f32_16x16x32_bf16 v[68:71], v[156:159], v[228:231], v[68:71]
	v_mfma_f32_16x16x32_bf16 v[64:67], v[170:173], v[228:231], v[64:67]
	s_setprio 0
	s_barrier
	s_setprio 2
	s_add_i32 s20, s52, s55
	v_lshl_add_u64 v[164:165], s[40:41], 0, v[134:135]
	s_mov_b32 m0, s20
	ds_read_b128 v[174:177], v169 offset:16384
	ds_read_b128 v[178:181], v169 offset:17408
	ds_read_b128 v[182:185], v169 offset:18432
	ds_read_b128 v[202:205], v169 offset:19456
	ds_read_b128 v[216:219], v169 offset:20480
	ds_read_b128 v[220:223], v169 offset:21504
	ds_read_b128 v[224:227], v169 offset:22528
	ds_read_b128 v[228:231], v169 offset:23552
	global_load_lds_dwordx4 v[164:165], off
	s_add_i32 m0, s20, 0x2000
	s_add_u32 s20, s40, 0x40000
	v_lshl_add_u64 v[186:187], s[40:41], 0, v[132:133]
	s_addc_u32 s21, s41, 0
	s_add_i32 s52, s53, s55
	global_load_lds_dwordx4 v[186:187], off
	v_lshl_add_u64 v[194:195], s[20:21], 0, v[134:135]
	s_mov_b32 m0, s52
	v_lshl_add_u64 v[196:197], s[58:59], 0, v[132:133]
	global_load_lds_dwordx4 v[194:195], off
	v_lshl_add_u64 v[194:195], s[20:21], 0, v[132:133]
	s_add_i32 m0, s52, 0x2000
	s_nop 0
	global_load_lds_dwordx4 v[194:195], off
	v_lshl_add_u64 v[194:195], s[58:59], 0, v[134:135]
	s_mov_b32 m0, s46
	s_nop 0
	global_load_lds_dwordx4 v[194:195], off
	s_mov_b32 m0, s47
	s_nop 0
	global_load_lds_dwordx4 v[196:197], off
	s_waitcnt vmcnt(8)
	s_waitcnt lgkmcnt(0)
	s_barrier
	s_setprio 1
	s_waitcnt lgkmcnt(0)
	v_mfma_f32_16x16x32_bf16 v[60:63], v[128:131], v[174:177], v[60:63]
	v_mfma_f32_16x16x32_bf16 v[56:59], v[144:147], v[174:177], v[56:59]
	v_mfma_f32_16x16x32_bf16 v[44:47], v[128:131], v[182:185], v[44:47]
	v_mfma_f32_16x16x32_bf16 v[40:43], v[144:147], v[182:185], v[40:43]
	v_mfma_f32_16x16x32_bf16 v[28:31], v[128:131], v[216:219], v[28:31]
	v_mfma_f32_16x16x32_bf16 v[24:27], v[144:147], v[216:219], v[24:27]
	v_mfma_f32_16x16x32_bf16 v[12:15], v[128:131], v[224:227], v[12:15]
	v_mfma_f32_16x16x32_bf16 v[8:11], v[144:147], v[224:227], v[8:11]
	v_mfma_f32_16x16x32_bf16 v[60:63], v[140:143], v[178:181], v[60:63]
	v_mfma_f32_16x16x32_bf16 v[56:59], v[148:151], v[178:181], v[56:59]
	v_mfma_f32_16x16x32_bf16 v[44:47], v[140:143], v[202:205], v[44:47]
	v_mfma_f32_16x16x32_bf16 v[40:43], v[148:151], v[202:205], v[40:43]
	v_mfma_f32_16x16x32_bf16 v[28:31], v[140:143], v[220:223], v[28:31]
	v_mfma_f32_16x16x32_bf16 v[24:27], v[148:151], v[220:223], v[24:27]
	v_mfma_f32_16x16x32_bf16 v[12:15], v[140:143], v[228:231], v[12:15]
	v_mfma_f32_16x16x32_bf16 v[8:11], v[148:151], v[228:231], v[8:11]
	s_setprio 0
	s_setprio 1
	v_mfma_f32_16x16x32_bf16 v[52:55], v[152:155], v[174:177], v[52:55]
	v_mfma_f32_16x16x32_bf16 v[48:51], v[160:163], v[174:177], v[48:51]
	v_mfma_f32_16x16x32_bf16 v[36:39], v[152:155], v[182:185], v[36:39]
	v_mfma_f32_16x16x32_bf16 v[32:35], v[160:163], v[182:185], v[32:35]
	v_mfma_f32_16x16x32_bf16 v[20:23], v[152:155], v[216:219], v[20:23]
	v_mfma_f32_16x16x32_bf16 v[16:19], v[160:163], v[216:219], v[16:19]
	v_mfma_f32_16x16x32_bf16 v[4:7], v[152:155], v[224:227], v[4:7]
	v_mfma_f32_16x16x32_bf16 v[0:3], v[160:163], v[224:227], v[0:3]
	v_mfma_f32_16x16x32_bf16 v[52:55], v[156:159], v[178:181], v[52:55]
	v_mfma_f32_16x16x32_bf16 v[48:51], v[170:173], v[178:181], v[48:51]
	v_mfma_f32_16x16x32_bf16 v[36:39], v[156:159], v[202:205], v[36:39]
	v_mfma_f32_16x16x32_bf16 v[32:35], v[170:173], v[202:205], v[32:35]
	v_mfma_f32_16x16x32_bf16 v[20:23], v[156:159], v[220:223], v[20:23]
	v_mfma_f32_16x16x32_bf16 v[16:19], v[170:173], v[220:223], v[16:19]
	v_mfma_f32_16x16x32_bf16 v[4:7], v[156:159], v[228:231], v[4:7]
	v_mfma_f32_16x16x32_bf16 v[0:3], v[170:173], v[228:231], v[0:3]
	s_setprio 0
	s_barrier
	s_setprio 2
	s_add_i32 s52, 0, 0x18000
	s_add_i32 s53, 0, 0x1c000
	v_add_u32_e32 v148, s52, v168
	v_add_u32_e32 v170, s53, v168
	ds_read_b128 v[128:131], v148
	ds_read_b128 v[140:143], v148 offset:1024
	ds_read_b128 v[144:147], v148 offset:2048
	ds_read_b128 v[148:151], v148 offset:3072
	ds_read_b128 v[152:155], v170
	ds_read_b128 v[156:159], v170 offset:1024
	ds_read_b128 v[160:163], v170 offset:2048
	ds_read_b128 v[170:173], v170 offset:3072
	s_add_u32 s20, s58, 0x40000
	s_addc_u32 s21, s59, 0
	s_mov_b32 m0, s25
	v_lshl_add_u64 v[232:233], s[20:21], 0, v[134:135]
	ds_read_b128 v[174:177], v169 offset:32768
	ds_read_b128 v[178:181], v169 offset:33792
	ds_read_b128 v[182:185], v169 offset:34816
	ds_read_b128 v[202:205], v169 offset:35840
	ds_read_b128 v[216:219], v169 offset:36864
	ds_read_b128 v[220:223], v169 offset:37888
	ds_read_b128 v[224:227], v169 offset:38912
	ds_read_b128 v[228:231], v169 offset:39936
	global_load_lds_dwordx4 v[232:233], off
	v_lshl_add_u64 v[232:233], s[20:21], 0, v[132:133]
	s_mov_b32 m0, s44
	s_nop 0
	global_load_lds_dwordx4 v[232:233], off
	s_waitcnt vmcnt(8)
	s_waitcnt lgkmcnt(0)
	s_barrier
	s_setprio 1
	s_waitcnt lgkmcnt(0)
	v_mfma_f32_16x16x32_bf16 v[120:123], v[128:131], v[174:177], v[120:123]
	v_mfma_f32_16x16x32_bf16 v[124:127], v[144:147], v[174:177], v[124:127]
	v_mfma_f32_16x16x32_bf16 v[108:111], v[128:131], v[182:185], v[108:111]
	v_mfma_f32_16x16x32_bf16 v[104:107], v[144:147], v[182:185], v[104:107]
	v_mfma_f32_16x16x32_bf16 v[92:95], v[128:131], v[216:219], v[92:95]
	v_mfma_f32_16x16x32_bf16 v[88:91], v[144:147], v[216:219], v[88:91]
	v_mfma_f32_16x16x32_bf16 v[76:79], v[128:131], v[224:227], v[76:79]
	v_mfma_f32_16x16x32_bf16 v[72:75], v[144:147], v[224:227], v[72:75]
	v_mfma_f32_16x16x32_bf16 v[120:123], v[140:143], v[178:181], v[120:123]
	v_mfma_f32_16x16x32_bf16 v[124:127], v[148:151], v[178:181], v[124:127]
	v_mfma_f32_16x16x32_bf16 v[108:111], v[140:143], v[202:205], v[108:111]
	v_mfma_f32_16x16x32_bf16 v[104:107], v[148:151], v[202:205], v[104:107]
	v_mfma_f32_16x16x32_bf16 v[92:95], v[140:143], v[220:223], v[92:95]
	v_mfma_f32_16x16x32_bf16 v[88:91], v[148:151], v[220:223], v[88:91]
	v_mfma_f32_16x16x32_bf16 v[76:79], v[140:143], v[228:231], v[76:79]
	v_mfma_f32_16x16x32_bf16 v[72:75], v[148:151], v[228:231], v[72:75]
	s_setprio 0
	s_setprio 1
	v_mfma_f32_16x16x32_bf16 v[116:119], v[152:155], v[174:177], v[116:119]
	v_mfma_f32_16x16x32_bf16 v[112:115], v[160:163], v[174:177], v[112:115]
	v_mfma_f32_16x16x32_bf16 v[100:103], v[152:155], v[182:185], v[100:103]
	v_mfma_f32_16x16x32_bf16 v[96:99], v[160:163], v[182:185], v[96:99]
	v_mfma_f32_16x16x32_bf16 v[84:87], v[152:155], v[216:219], v[84:87]
	v_mfma_f32_16x16x32_bf16 v[80:83], v[160:163], v[216:219], v[80:83]
	v_mfma_f32_16x16x32_bf16 v[68:71], v[152:155], v[224:227], v[68:71]
	v_mfma_f32_16x16x32_bf16 v[64:67], v[160:163], v[224:227], v[64:67]
	v_mfma_f32_16x16x32_bf16 v[116:119], v[156:159], v[178:181], v[116:119]
	v_mfma_f32_16x16x32_bf16 v[112:115], v[170:173], v[178:181], v[112:115]
	v_mfma_f32_16x16x32_bf16 v[100:103], v[156:159], v[202:205], v[100:103]
	v_mfma_f32_16x16x32_bf16 v[96:99], v[170:173], v[202:205], v[96:99]
	v_mfma_f32_16x16x32_bf16 v[84:87], v[156:159], v[220:223], v[84:87]
	v_mfma_f32_16x16x32_bf16 v[80:83], v[170:173], v[220:223], v[80:83]
	v_mfma_f32_16x16x32_bf16 v[68:71], v[156:159], v[228:231], v[68:71]
	v_mfma_f32_16x16x32_bf16 v[64:67], v[170:173], v[228:231], v[64:67]
	s_setprio 0
	s_barrier
	s_setprio 2
	s_add_i32 s20, s52, s55
	v_lshl_add_u64 v[164:165], v[164:165], 0, s[62:63]
	s_mov_b32 m0, s20
	ds_read_b128 v[174:177], v169 offset:49152
	ds_read_b128 v[178:181], v169 offset:50176
	ds_read_b128 v[182:185], v169 offset:51200
	ds_read_b128 v[202:205], v169 offset:52224
	ds_read_b128 v[216:219], v169 offset:53248
	ds_read_b128 v[220:223], v169 offset:54272
	ds_read_b128 v[224:227], v169 offset:55296
	ds_read_b128 v[228:231], v169 offset:56320
	global_load_lds_dwordx4 v[164:165], off
	s_add_i32 m0, s20, 0x2000
	s_add_u32 s20, s40, 0x40080
	v_lshl_add_u64 v[164:165], v[186:187], 0, s[62:63]
	s_addc_u32 s21, s41, 0
	s_add_i32 s40, s53, s55
	global_load_lds_dwordx4 v[164:165], off
	v_lshl_add_u64 v[164:165], s[20:21], 0, v[134:135]
	s_mov_b32 m0, s40
	s_nop 0
	global_load_lds_dwordx4 v[164:165], off
	v_lshl_add_u64 v[164:165], s[20:21], 0, v[132:133]
	s_add_i32 m0, s40, 0x2000
	s_nop 0
	global_load_lds_dwordx4 v[164:165], off
	v_lshl_add_u64 v[164:165], v[194:195], 0, s[62:63]
	s_mov_b32 m0, s56
	s_nop 0
	global_load_lds_dwordx4 v[164:165], off
	v_lshl_add_u64 v[164:165], v[196:197], 0, s[62:63]
	s_mov_b32 m0, s57
	s_nop 0
	global_load_lds_dwordx4 v[164:165], off
	s_waitcnt vmcnt(8)
	s_waitcnt lgkmcnt(0)
	s_barrier
	s_setprio 1
	s_waitcnt lgkmcnt(0)
	v_mfma_f32_16x16x32_bf16 v[60:63], v[128:131], v[174:177], v[60:63]
	v_mfma_f32_16x16x32_bf16 v[56:59], v[144:147], v[174:177], v[56:59]
	v_mfma_f32_16x16x32_bf16 v[44:47], v[128:131], v[182:185], v[44:47]
	v_mfma_f32_16x16x32_bf16 v[40:43], v[144:147], v[182:185], v[40:43]
	v_mfma_f32_16x16x32_bf16 v[28:31], v[128:131], v[216:219], v[28:31]
	v_mfma_f32_16x16x32_bf16 v[24:27], v[144:147], v[216:219], v[24:27]
	v_mfma_f32_16x16x32_bf16 v[12:15], v[128:131], v[224:227], v[12:15]
	v_mfma_f32_16x16x32_bf16 v[8:11], v[144:147], v[224:227], v[8:11]
	v_mfma_f32_16x16x32_bf16 v[60:63], v[140:143], v[178:181], v[60:63]
	v_mfma_f32_16x16x32_bf16 v[56:59], v[148:151], v[178:181], v[56:59]
	v_mfma_f32_16x16x32_bf16 v[44:47], v[140:143], v[202:205], v[44:47]
	v_mfma_f32_16x16x32_bf16 v[40:43], v[148:151], v[202:205], v[40:43]
	v_mfma_f32_16x16x32_bf16 v[28:31], v[140:143], v[220:223], v[28:31]
	v_mfma_f32_16x16x32_bf16 v[24:27], v[148:151], v[220:223], v[24:27]
	v_mfma_f32_16x16x32_bf16 v[12:15], v[140:143], v[228:231], v[12:15]
	v_mfma_f32_16x16x32_bf16 v[8:11], v[148:151], v[228:231], v[8:11]
	s_setprio 0
	s_setprio 1
	v_mfma_f32_16x16x32_bf16 v[52:55], v[152:155], v[174:177], v[52:55]
	v_mfma_f32_16x16x32_bf16 v[48:51], v[160:163], v[174:177], v[48:51]
	v_mfma_f32_16x16x32_bf16 v[36:39], v[152:155], v[182:185], v[36:39]
	v_mfma_f32_16x16x32_bf16 v[32:35], v[160:163], v[182:185], v[32:35]
	v_mfma_f32_16x16x32_bf16 v[20:23], v[152:155], v[216:219], v[20:23]
	v_mfma_f32_16x16x32_bf16 v[16:19], v[160:163], v[216:219], v[16:19]
	v_mfma_f32_16x16x32_bf16 v[4:7], v[152:155], v[224:227], v[4:7]
	v_mfma_f32_16x16x32_bf16 v[0:3], v[160:163], v[224:227], v[0:3]
	v_mfma_f32_16x16x32_bf16 v[52:55], v[156:159], v[178:181], v[52:55]
	v_mfma_f32_16x16x32_bf16 v[48:51], v[170:173], v[178:181], v[48:51]
	v_mfma_f32_16x16x32_bf16 v[36:39], v[156:159], v[202:205], v[36:39]
	v_mfma_f32_16x16x32_bf16 v[32:35], v[170:173], v[202:205], v[32:35]
	v_mfma_f32_16x16x32_bf16 v[20:23], v[156:159], v[220:223], v[20:23]
	v_mfma_f32_16x16x32_bf16 v[16:19], v[170:173], v[220:223], v[16:19]
	v_mfma_f32_16x16x32_bf16 v[4:7], v[156:159], v[228:231], v[4:7]
	v_mfma_f32_16x16x32_bf16 v[0:3], v[170:173], v[228:231], v[0:3]
	s_setprio 0
	s_barrier
	s_setprio 2
	s_add_u32 s38, s38, 0x100
	s_addc_u32 s39, s39, 0
	s_add_u32 s82, s82, 0x100
	s_addc_u32 s83, s83, 0
	s_cmp_ge_i32 s61, s80
	s_mov_b32 s40, s61
	s_cbranch_scc0 .LBB0_247
	s_setprio 0

.LBB0_294:
	s_add_i32 vcc_lo, s82, 2
	s_add_u32 s20, s66, 0xfffc0080
	s_addc_u32 s21, s67, -1
	s_add_i32 vcc_hi, 0, 0x10000
	s_cmp_eq_u32 s60, s82
	s_cselect_b32 s87, s39, s21
	s_cselect_b32 s86, s41, s20
	v_add_u32_e32 v148, vcc_hi, v151
	s_cselect_b32 s83, s88, s95
	s_cselect_b32 s82, s89, s94
	s_add_i32 s52, 0, 0x14000
	ds_read_b128 v[140:143], v148
	ds_read_b128 v[144:147], v148 offset:1024
	ds_read_b128 v[154:157], v148 offset:2048
	ds_read_b128 v[158:161], v148 offset:3072
	v_add_u32_e32 v148, s52, v151
	ds_read_b128 v[162:165], v148
	ds_read_b128 v[166:169], v148 offset:1024
	ds_read_b128 v[170:173], v148 offset:2048
	ds_read_b128 v[174:177], v148 offset:3072
	v_lshl_add_u64 v[186:187], s[66:67], 0, v[136:137]
	s_add_i32 m0, s13, 0xc000
	ds_read_b128 v[178:181], v152
	ds_read_b128 v[182:185], v152 offset:1024
	ds_read_b128 v[202:205], v152 offset:2048
	ds_read_b128 v[216:219], v152 offset:3072
	ds_read_b128 v[220:223], v152 offset:4096
	ds_read_b128 v[224:227], v152 offset:5120
	ds_read_b128 v[228:231], v152 offset:6144
	ds_read_b128 v[232:235], v152 offset:7168
	global_load_lds_dwordx4 v[186:187], off
	v_lshl_add_u64 v[186:187], s[66:67], 0, v[138:139]
	s_add_i32 m0, s13, 0xe000
	s_nop 0
	global_load_lds_dwordx4 v[186:187], off
	s_waitcnt vmcnt(8)
	s_waitcnt lgkmcnt(0)
	s_barrier
	s_setprio 1
	s_waitcnt lgkmcnt(0)
	v_mfma_f32_16x16x32_bf16 v[120:123], v[140:143], v[178:181], v[120:123]
	v_mfma_f32_16x16x32_bf16 v[124:127], v[154:157], v[178:181], v[124:127]
	v_mfma_f32_16x16x32_bf16 v[108:111], v[140:143], v[202:205], v[108:111]
	v_mfma_f32_16x16x32_bf16 v[104:107], v[154:157], v[202:205], v[104:107]
	v_mfma_f32_16x16x32_bf16 v[92:95], v[140:143], v[220:223], v[92:95]
	v_mfma_f32_16x16x32_bf16 v[88:91], v[154:157], v[220:223], v[88:91]
	v_mfma_f32_16x16x32_bf16 v[76:79], v[140:143], v[228:231], v[76:79]
	v_mfma_f32_16x16x32_bf16 v[72:75], v[154:157], v[228:231], v[72:75]
	v_mfma_f32_16x16x32_bf16 v[120:123], v[144:147], v[182:185], v[120:123]
	v_mfma_f32_16x16x32_bf16 v[124:127], v[158:161], v[182:185], v[124:127]
	v_mfma_f32_16x16x32_bf16 v[108:111], v[144:147], v[216:219], v[108:111]
	v_mfma_f32_16x16x32_bf16 v[104:107], v[158:161], v[216:219], v[104:107]
	v_mfma_f32_16x16x32_bf16 v[92:95], v[144:147], v[224:227], v[92:95]
	v_mfma_f32_16x16x32_bf16 v[88:91], v[158:161], v[224:227], v[88:91]
	v_mfma_f32_16x16x32_bf16 v[76:79], v[144:147], v[232:235], v[76:79]
	v_mfma_f32_16x16x32_bf16 v[72:75], v[158:161], v[232:235], v[72:75]
	s_setprio 0
	s_setprio 1
	v_mfma_f32_16x16x32_bf16 v[116:119], v[162:165], v[178:181], v[116:119]
	v_mfma_f32_16x16x32_bf16 v[112:115], v[170:173], v[178:181], v[112:115]
	v_mfma_f32_16x16x32_bf16 v[100:103], v[162:165], v[202:205], v[100:103]
	v_mfma_f32_16x16x32_bf16 v[96:99], v[170:173], v[202:205], v[96:99]
	v_mfma_f32_16x16x32_bf16 v[84:87], v[162:165], v[220:223], v[84:87]
	v_mfma_f32_16x16x32_bf16 v[80:83], v[170:173], v[220:223], v[80:83]
	v_mfma_f32_16x16x32_bf16 v[68:71], v[162:165], v[228:231], v[68:71]
	v_mfma_f32_16x16x32_bf16 v[64:67], v[170:173], v[228:231], v[64:67]
	v_mfma_f32_16x16x32_bf16 v[116:119], v[166:169], v[182:185], v[116:119]
	v_mfma_f32_16x16x32_bf16 v[112:115], v[174:177], v[182:185], v[112:115]
	v_mfma_f32_16x16x32_bf16 v[100:103], v[166:169], v[216:219], v[100:103]
	v_mfma_f32_16x16x32_bf16 v[96:99], v[174:177], v[216:219], v[96:99]
	v_mfma_f32_16x16x32_bf16 v[84:87], v[166:169], v[224:227], v[84:87]
	v_mfma_f32_16x16x32_bf16 v[80:83], v[174:177], v[224:227], v[80:83]
	v_mfma_f32_16x16x32_bf16 v[68:71], v[166:169], v[232:235], v[68:71]
	v_mfma_f32_16x16x32_bf16 v[64:67], v[174:177], v[232:235], v[64:67]
	s_setprio 0
	s_barrier
	s_setprio 2
	s_add_i32 s20, vcc_hi, s12
	v_lshl_add_u64 v[186:187], s[82:83], 0, v[132:133]
	s_mov_b32 m0, s20
	ds_read_b128 v[178:181], v152 offset:16384
	ds_read_b128 v[182:185], v152 offset:17408
	ds_read_b128 v[202:205], v152 offset:18432
	ds_read_b128 v[216:219], v152 offset:19456
	ds_read_b128 v[220:223], v152 offset:20480
	ds_read_b128 v[224:227], v152 offset:21504
	ds_read_b128 v[228:231], v152 offset:22528
	ds_read_b128 v[232:235], v152 offset:23552
	global_load_lds_dwordx4 v[186:187], off
	s_add_i32 m0, s20, 0x2000
	s_add_u32 s20, s82, 0x40000
	v_lshl_add_u64 v[194:195], s[82:83], 0, v[128:129]
	s_addc_u32 s21, s83, 0
	s_add_i32 s52, s52, s12
	global_load_lds_dwordx4 v[194:195], off
	v_lshl_add_u64 v[196:197], s[20:21], 0, v[132:133]
	s_mov_b32 m0, s52
	v_lshl_add_u64 v[236:237], s[86:87], 0, v[130:131]
	global_load_lds_dwordx4 v[196:197], off
	v_lshl_add_u64 v[196:197], s[20:21], 0, v[128:129]
	s_add_i32 m0, s52, 0x2000
	s_nop 0
	global_load_lds_dwordx4 v[196:197], off
	v_lshl_add_u64 v[196:197], s[86:87], 0, v[134:135]
	s_mov_b32 m0, s13
	s_nop 0
	global_load_lds_dwordx4 v[196:197], off
	s_mov_b32 m0, s28
	s_nop 0
	global_load_lds_dwordx4 v[236:237], off
	s_waitcnt vmcnt(8)
	s_waitcnt lgkmcnt(0)
	s_barrier
	s_setprio 1
	s_waitcnt lgkmcnt(0)
	v_mfma_f32_16x16x32_bf16 v[60:63], v[140:143], v[178:181], v[60:63]
	v_mfma_f32_16x16x32_bf16 v[56:59], v[154:157], v[178:181], v[56:59]
	v_mfma_f32_16x16x32_bf16 v[44:47], v[140:143], v[202:205], v[44:47]
	v_mfma_f32_16x16x32_bf16 v[40:43], v[154:157], v[202:205], v[40:43]
	v_mfma_f32_16x16x32_bf16 v[28:31], v[140:143], v[220:223], v[28:31]
	v_mfma_f32_16x16x32_bf16 v[24:27], v[154:157], v[220:223], v[24:27]
	v_mfma_f32_16x16x32_bf16 v[12:15], v[140:143], v[228:231], v[12:15]
	v_mfma_f32_16x16x32_bf16 v[8:11], v[154:157], v[228:231], v[8:11]
	v_mfma_f32_16x16x32_bf16 v[60:63], v[144:147], v[182:185], v[60:63]
	v_mfma_f32_16x16x32_bf16 v[56:59], v[158:161], v[182:185], v[56:59]
	v_mfma_f32_16x16x32_bf16 v[44:47], v[144:147], v[216:219], v[44:47]
	v_mfma_f32_16x16x32_bf16 v[40:43], v[158:161], v[216:219], v[40:43]
	v_mfma_f32_16x16x32_bf16 v[28:31], v[144:147], v[224:227], v[28:31]
	v_mfma_f32_16x16x32_bf16 v[24:27], v[158:161], v[224:227], v[24:27]
	v_mfma_f32_16x16x32_bf16 v[12:15], v[144:147], v[232:235], v[12:15]
	v_mfma_f32_16x16x32_bf16 v[8:11], v[158:161], v[232:235], v[8:11]
	s_setprio 0
	s_setprio 1
	v_mfma_f32_16x16x32_bf16 v[52:55], v[162:165], v[178:181], v[52:55]
	v_mfma_f32_16x16x32_bf16 v[48:51], v[170:173], v[178:181], v[48:51]
	v_mfma_f32_16x16x32_bf16 v[36:39], v[162:165], v[202:205], v[36:39]
	v_mfma_f32_16x16x32_bf16 v[32:35], v[170:173], v[202:205], v[32:35]
	v_mfma_f32_16x16x32_bf16 v[20:23], v[162:165], v[220:223], v[20:23]
	v_mfma_f32_16x16x32_bf16 v[16:19], v[170:173], v[220:223], v[16:19]
	v_mfma_f32_16x16x32_bf16 v[4:7], v[162:165], v[228:231], v[4:7]
	v_mfma_f32_16x16x32_bf16 v[0:3], v[170:173], v[228:231], v[0:3]
	v_mfma_f32_16x16x32_bf16 v[52:55], v[166:169], v[182:185], v[52:55]
	v_mfma_f32_16x16x32_bf16 v[48:51], v[174:177], v[182:185], v[48:51]
	v_mfma_f32_16x16x32_bf16 v[36:39], v[166:169], v[216:219], v[36:39]
	v_mfma_f32_16x16x32_bf16 v[32:35], v[174:177], v[216:219], v[32:35]
	v_mfma_f32_16x16x32_bf16 v[20:23], v[166:169], v[224:227], v[20:23]
	v_mfma_f32_16x16x32_bf16 v[16:19], v[174:177], v[224:227], v[16:19]
	v_mfma_f32_16x16x32_bf16 v[4:7], v[166:169], v[232:235], v[4:7]
	v_mfma_f32_16x16x32_bf16 v[0:3], v[174:177], v[232:235], v[0:3]
	s_setprio 0
	s_barrier
	s_setprio 2
	s_add_i32 s52, 0, 0x18000
	v_add_u32_e32 v148, s52, v151
	s_add_i32 s53, 0, 0x1c000
	ds_read_b128 v[140:143], v148
	ds_read_b128 v[144:147], v148 offset:1024
	ds_read_b128 v[154:157], v148 offset:2048
	ds_read_b128 v[158:161], v148 offset:3072
	v_add_u32_e32 v148, s53, v151
	ds_read_b128 v[162:165], v148
	ds_read_b128 v[166:169], v148 offset:1024
	ds_read_b128 v[170:173], v148 offset:2048
	ds_read_b128 v[174:177], v148 offset:3072
	s_add_u32 s20, s86, 0x40000
	s_addc_u32 s21, s87, 0
	s_mov_b32 m0, s46
	v_lshl_add_u64 v[238:239], s[20:21], 0, v[134:135]
	ds_read_b128 v[178:181], v152 offset:32768
	ds_read_b128 v[182:185], v152 offset:33792
	ds_read_b128 v[202:205], v152 offset:34816
	ds_read_b128 v[216:219], v152 offset:35840
	ds_read_b128 v[220:223], v152 offset:36864
	ds_read_b128 v[224:227], v152 offset:37888
	ds_read_b128 v[228:231], v152 offset:38912
	ds_read_b128 v[232:235], v152 offset:39936
	global_load_lds_dwordx4 v[238:239], off
	v_lshl_add_u64 v[238:239], s[20:21], 0, v[130:131]
	s_mov_b32 m0, s47
	s_nop 0
	global_load_lds_dwordx4 v[238:239], off
	s_waitcnt vmcnt(8)
	s_waitcnt lgkmcnt(0)
	s_barrier
	s_setprio 1
	s_waitcnt lgkmcnt(0)
	v_mfma_f32_16x16x32_bf16 v[120:123], v[140:143], v[178:181], v[120:123]
	v_mfma_f32_16x16x32_bf16 v[124:127], v[154:157], v[178:181], v[124:127]
	v_mfma_f32_16x16x32_bf16 v[108:111], v[140:143], v[202:205], v[108:111]
	v_mfma_f32_16x16x32_bf16 v[104:107], v[154:157], v[202:205], v[104:107]
	v_mfma_f32_16x16x32_bf16 v[92:95], v[140:143], v[220:223], v[92:95]
	v_mfma_f32_16x16x32_bf16 v[88:91], v[154:157], v[220:223], v[88:91]
	v_mfma_f32_16x16x32_bf16 v[76:79], v[140:143], v[228:231], v[76:79]
	v_mfma_f32_16x16x32_bf16 v[72:75], v[154:157], v[228:231], v[72:75]
	v_mfma_f32_16x16x32_bf16 v[120:123], v[144:147], v[182:185], v[120:123]
	v_mfma_f32_16x16x32_bf16 v[124:127], v[158:161], v[182:185], v[124:127]
	v_mfma_f32_16x16x32_bf16 v[108:111], v[144:147], v[216:219], v[108:111]
	v_mfma_f32_16x16x32_bf16 v[104:107], v[158:161], v[216:219], v[104:107]
	v_mfma_f32_16x16x32_bf16 v[92:95], v[144:147], v[224:227], v[92:95]
	v_mfma_f32_16x16x32_bf16 v[88:91], v[158:161], v[224:227], v[88:91]
	v_mfma_f32_16x16x32_bf16 v[76:79], v[144:147], v[232:235], v[76:79]
	v_mfma_f32_16x16x32_bf16 v[72:75], v[158:161], v[232:235], v[72:75]
	s_setprio 0
	s_setprio 1
	v_mfma_f32_16x16x32_bf16 v[116:119], v[162:165], v[178:181], v[116:119]
	v_mfma_f32_16x16x32_bf16 v[112:115], v[170:173], v[178:181], v[112:115]
	v_mfma_f32_16x16x32_bf16 v[100:103], v[162:165], v[202:205], v[100:103]
	v_mfma_f32_16x16x32_bf16 v[96:99], v[170:173], v[202:205], v[96:99]
	v_mfma_f32_16x16x32_bf16 v[84:87], v[162:165], v[220:223], v[84:87]
	v_mfma_f32_16x16x32_bf16 v[80:83], v[170:173], v[220:223], v[80:83]
	v_mfma_f32_16x16x32_bf16 v[68:71], v[162:165], v[228:231], v[68:71]
	v_mfma_f32_16x16x32_bf16 v[64:67], v[170:173], v[228:231], v[64:67]
	v_mfma_f32_16x16x32_bf16 v[116:119], v[166:169], v[182:185], v[116:119]
	v_mfma_f32_16x16x32_bf16 v[112:115], v[174:177], v[182:185], v[112:115]
	v_mfma_f32_16x16x32_bf16 v[100:103], v[166:169], v[216:219], v[100:103]
	v_mfma_f32_16x16x32_bf16 v[96:99], v[174:177], v[216:219], v[96:99]
	v_mfma_f32_16x16x32_bf16 v[84:87], v[166:169], v[224:227], v[84:87]
	v_mfma_f32_16x16x32_bf16 v[80:83], v[174:177], v[224:227], v[80:83]
	v_mfma_f32_16x16x32_bf16 v[68:71], v[166:169], v[232:235], v[68:71]
	v_mfma_f32_16x16x32_bf16 v[64:67], v[174:177], v[232:235], v[64:67]
	s_setprio 0
	s_barrier
	s_setprio 2
	s_add_i32 s20, s52, s12
	v_lshl_add_u64 v[186:187], v[186:187], 0, s[62:63]
	s_mov_b32 m0, s20
	ds_read_b128 v[178:181], v152 offset:49152
	ds_read_b128 v[182:185], v152 offset:50176
	ds_read_b128 v[202:205], v152 offset:51200
	ds_read_b128 v[216:219], v152 offset:52224
	ds_read_b128 v[220:223], v152 offset:53248
	ds_read_b128 v[224:227], v152 offset:54272
	ds_read_b128 v[228:231], v152 offset:55296
	ds_read_b128 v[232:235], v152 offset:56320
	global_load_lds_dwordx4 v[186:187], off
	s_add_i32 m0, s20, 0x2000
	s_add_u32 s20, s82, 0x40080
	v_lshl_add_u64 v[186:187], v[194:195], 0, s[62:63]
	s_addc_u32 s21, s83, 0
	s_add_i32 s52, s53, s12
	global_load_lds_dwordx4 v[186:187], off
	v_lshl_add_u64 v[186:187], s[20:21], 0, v[132:133]
	s_mov_b32 m0, s52
	s_nop 0
	global_load_lds_dwordx4 v[186:187], off
	v_lshl_add_u64 v[186:187], s[20:21], 0, v[128:129]
	s_add_i32 m0, s52, 0x2000
	s_nop 0
	global_load_lds_dwordx4 v[186:187], off
	v_lshl_add_u64 v[186:187], v[196:197], 0, s[62:63]
	s_mov_b32 m0, s48
	s_nop 0
	global_load_lds_dwordx4 v[186:187], off
	v_lshl_add_u64 v[186:187], v[236:237], 0, s[62:63]
	s_mov_b32 m0, s49
	s_nop 0
	global_load_lds_dwordx4 v[186:187], off
	s_waitcnt vmcnt(8)
	s_waitcnt lgkmcnt(0)
	s_barrier
	s_setprio 1
	s_waitcnt lgkmcnt(0)
	v_mfma_f32_16x16x32_bf16 v[60:63], v[140:143], v[178:181], v[60:63]
	v_mfma_f32_16x16x32_bf16 v[56:59], v[154:157], v[178:181], v[56:59]
	v_mfma_f32_16x16x32_bf16 v[44:47], v[140:143], v[202:205], v[44:47]
	v_mfma_f32_16x16x32_bf16 v[40:43], v[154:157], v[202:205], v[40:43]
	v_mfma_f32_16x16x32_bf16 v[28:31], v[140:143], v[220:223], v[28:31]
	v_mfma_f32_16x16x32_bf16 v[24:27], v[154:157], v[220:223], v[24:27]
	v_mfma_f32_16x16x32_bf16 v[12:15], v[140:143], v[228:231], v[12:15]
	v_mfma_f32_16x16x32_bf16 v[8:11], v[154:157], v[228:231], v[8:11]
	v_mfma_f32_16x16x32_bf16 v[60:63], v[144:147], v[182:185], v[60:63]
	v_mfma_f32_16x16x32_bf16 v[56:59], v[158:161], v[182:185], v[56:59]
	v_mfma_f32_16x16x32_bf16 v[44:47], v[144:147], v[216:219], v[44:47]
	v_mfma_f32_16x16x32_bf16 v[40:43], v[158:161], v[216:219], v[40:43]
	v_mfma_f32_16x16x32_bf16 v[28:31], v[144:147], v[224:227], v[28:31]
	v_mfma_f32_16x16x32_bf16 v[24:27], v[158:161], v[224:227], v[24:27]
	v_mfma_f32_16x16x32_bf16 v[12:15], v[144:147], v[232:235], v[12:15]
	v_mfma_f32_16x16x32_bf16 v[8:11], v[158:161], v[232:235], v[8:11]
	s_setprio 0
	s_setprio 1
	v_mfma_f32_16x16x32_bf16 v[52:55], v[162:165], v[178:181], v[52:55]
	v_mfma_f32_16x16x32_bf16 v[48:51], v[170:173], v[178:181], v[48:51]
	v_mfma_f32_16x16x32_bf16 v[36:39], v[162:165], v[202:205], v[36:39]
	v_mfma_f32_16x16x32_bf16 v[32:35], v[170:173], v[202:205], v[32:35]
	v_mfma_f32_16x16x32_bf16 v[20:23], v[162:165], v[220:223], v[20:23]
	v_mfma_f32_16x16x32_bf16 v[16:19], v[170:173], v[220:223], v[16:19]
	v_mfma_f32_16x16x32_bf16 v[4:7], v[162:165], v[228:231], v[4:7]
	v_mfma_f32_16x16x32_bf16 v[0:3], v[170:173], v[228:231], v[0:3]
	v_mfma_f32_16x16x32_bf16 v[52:55], v[166:169], v[182:185], v[52:55]
	v_mfma_f32_16x16x32_bf16 v[48:51], v[174:177], v[182:185], v[48:51]
	v_mfma_f32_16x16x32_bf16 v[36:39], v[166:169], v[216:219], v[36:39]
	v_mfma_f32_16x16x32_bf16 v[32:35], v[174:177], v[216:219], v[32:35]
	v_mfma_f32_16x16x32_bf16 v[20:23], v[166:169], v[224:227], v[20:23]
	v_mfma_f32_16x16x32_bf16 v[16:19], v[174:177], v[224:227], v[16:19]
	v_mfma_f32_16x16x32_bf16 v[4:7], v[166:169], v[232:235], v[4:7]
	v_mfma_f32_16x16x32_bf16 v[0:3], v[174:177], v[232:235], v[0:3]
	s_setprio 0
	s_barrier
	s_setprio 2
	s_add_u32 s66, s66, 0x100
	s_addc_u32 s67, s67, 0
	s_add_u32 s94, s94, 0x100
	s_addc_u32 s95, s95, 0
	s_cmp_ge_i32 vcc_lo, s55
	s_mov_b32 s82, vcc_lo
	s_cbranch_scc0 .LBB0_294
	s_setprio 0
	s_mov_b64 s[88:89], 0x8000

.LBB0_316:
	s_add_i32 vcc_lo, s82, 2
	s_add_u32 s20, s66, 0xfffc0080
	s_addc_u32 s21, s67, -1
	s_add_i32 s52, 0, 0x10000
	s_cmp_eq_u32 s60, s82
	s_cselect_b32 s87, s39, s21
	s_cselect_b32 s86, s41, s20
	s_cselect_b32 s83, s88, s95
	s_cselect_b32 s82, s89, s94
	s_add_i32 s53, 0, 0x14000
	v_add_u32_e32 v156, s52, v142
	v_add_u32_e32 v172, s53, v142
	ds_read_b128 v[144:147], v156
	ds_read_b128 v[148:151], v156 offset:1024
	ds_read_b128 v[152:155], v156 offset:2048
	ds_read_b128 v[156:159], v156 offset:3072
	ds_read_b128 v[160:163], v172
	ds_read_b128 v[164:167], v172 offset:1024
	ds_read_b128 v[168:171], v172 offset:2048
	ds_read_b128 v[172:175], v172 offset:3072
	v_lshl_add_u64 v[194:195], s[66:67], 0, v[136:137]
	s_add_i32 m0, s13, 0xc000
	ds_read_b128 v[176:179], v143
	ds_read_b128 v[180:183], v143 offset:1024
	ds_read_b128 v[184:187], v143 offset:2048
	ds_read_b128 v[202:205], v143 offset:3072
	ds_read_b128 v[216:219], v143 offset:4096
	ds_read_b128 v[220:223], v143 offset:5120
	ds_read_b128 v[224:227], v143 offset:6144
	ds_read_b128 v[228:231], v143 offset:7168
	global_load_lds_dwordx4 v[194:195], off
	v_lshl_add_u64 v[194:195], s[66:67], 0, v[138:139]
	s_add_i32 m0, s13, 0xe000
	s_nop 0
	global_load_lds_dwordx4 v[194:195], off
	s_waitcnt vmcnt(8)
	s_waitcnt lgkmcnt(0)
	s_barrier
	s_setprio 1
	s_waitcnt lgkmcnt(0)
	v_mfma_f32_16x16x32_bf16 v[124:127], v[144:147], v[176:179], v[124:127]
	v_mfma_f32_16x16x32_bf16 v[120:123], v[152:155], v[176:179], v[120:123]
	v_mfma_f32_16x16x32_bf16 v[108:111], v[144:147], v[184:187], v[108:111]
	v_mfma_f32_16x16x32_bf16 v[104:107], v[152:155], v[184:187], v[104:107]
	v_mfma_f32_16x16x32_bf16 v[92:95], v[144:147], v[216:219], v[92:95]
	v_mfma_f32_16x16x32_bf16 v[88:91], v[152:155], v[216:219], v[88:91]
	v_mfma_f32_16x16x32_bf16 v[76:79], v[144:147], v[224:227], v[76:79]
	v_mfma_f32_16x16x32_bf16 v[72:75], v[152:155], v[224:227], v[72:75]
	v_mfma_f32_16x16x32_bf16 v[124:127], v[148:151], v[180:183], v[124:127]
	v_mfma_f32_16x16x32_bf16 v[120:123], v[156:159], v[180:183], v[120:123]
	v_mfma_f32_16x16x32_bf16 v[108:111], v[148:151], v[202:205], v[108:111]
	v_mfma_f32_16x16x32_bf16 v[104:107], v[156:159], v[202:205], v[104:107]
	v_mfma_f32_16x16x32_bf16 v[92:95], v[148:151], v[220:223], v[92:95]
	v_mfma_f32_16x16x32_bf16 v[88:91], v[156:159], v[220:223], v[88:91]
	v_mfma_f32_16x16x32_bf16 v[76:79], v[148:151], v[228:231], v[76:79]
	v_mfma_f32_16x16x32_bf16 v[72:75], v[156:159], v[228:231], v[72:75]
	s_setprio 0
	s_setprio 1
	v_mfma_f32_16x16x32_bf16 v[116:119], v[160:163], v[176:179], v[116:119]
	v_mfma_f32_16x16x32_bf16 v[112:115], v[168:171], v[176:179], v[112:115]
	v_mfma_f32_16x16x32_bf16 v[100:103], v[160:163], v[184:187], v[100:103]
	v_mfma_f32_16x16x32_bf16 v[96:99], v[168:171], v[184:187], v[96:99]
	v_mfma_f32_16x16x32_bf16 v[84:87], v[160:163], v[216:219], v[84:87]
	v_mfma_f32_16x16x32_bf16 v[80:83], v[168:171], v[216:219], v[80:83]
	v_mfma_f32_16x16x32_bf16 v[68:71], v[160:163], v[224:227], v[68:71]
	v_mfma_f32_16x16x32_bf16 v[64:67], v[168:171], v[224:227], v[64:67]
	v_mfma_f32_16x16x32_bf16 v[116:119], v[164:167], v[180:183], v[116:119]
	v_mfma_f32_16x16x32_bf16 v[112:115], v[172:175], v[180:183], v[112:115]
	v_mfma_f32_16x16x32_bf16 v[100:103], v[164:167], v[202:205], v[100:103]
	v_mfma_f32_16x16x32_bf16 v[96:99], v[172:175], v[202:205], v[96:99]
	v_mfma_f32_16x16x32_bf16 v[84:87], v[164:167], v[220:223], v[84:87]
	v_mfma_f32_16x16x32_bf16 v[80:83], v[172:175], v[220:223], v[80:83]
	v_mfma_f32_16x16x32_bf16 v[68:71], v[164:167], v[228:231], v[68:71]
	v_mfma_f32_16x16x32_bf16 v[64:67], v[172:175], v[228:231], v[64:67]
	s_setprio 0
	s_barrier
	s_setprio 2
	s_add_i32 s20, s52, s12
	v_lshl_add_u64 v[194:195], s[82:83], 0, v[132:133]
	s_mov_b32 m0, s20
	ds_read_b128 v[176:179], v143 offset:16384
	ds_read_b128 v[180:183], v143 offset:17408
	ds_read_b128 v[184:187], v143 offset:18432
	ds_read_b128 v[202:205], v143 offset:19456
	ds_read_b128 v[216:219], v143 offset:20480
	ds_read_b128 v[220:223], v143 offset:21504
	ds_read_b128 v[224:227], v143 offset:22528
	ds_read_b128 v[228:231], v143 offset:23552
	global_load_lds_dwordx4 v[194:195], off
	s_add_i32 m0, s20, 0x2000
	s_add_u32 s20, s82, 0x40000
	v_lshl_add_u64 v[196:197], s[82:83], 0, v[128:129]
	s_addc_u32 s21, s83, 0
	s_add_i32 s52, s53, s12
	global_load_lds_dwordx4 v[196:197], off
	v_lshl_add_u64 v[232:233], s[20:21], 0, v[132:133]
	s_mov_b32 m0, s52
	v_lshl_add_u64 v[234:235], s[86:87], 0, v[130:131]
	global_load_lds_dwordx4 v[232:233], off
	v_lshl_add_u64 v[232:233], s[20:21], 0, v[128:129]
	s_add_i32 m0, s52, 0x2000
	s_nop 0
	global_load_lds_dwordx4 v[232:233], off
	v_lshl_add_u64 v[232:233], s[86:87], 0, v[134:135]
	s_mov_b32 m0, s13
	s_nop 0
	global_load_lds_dwordx4 v[232:233], off
	s_mov_b32 m0, s28
	s_nop 0
	global_load_lds_dwordx4 v[234:235], off
	s_waitcnt vmcnt(8)
	s_waitcnt lgkmcnt(0)
	s_barrier
	s_setprio 1
	s_waitcnt lgkmcnt(0)
	v_mfma_f32_16x16x32_bf16 v[60:63], v[144:147], v[176:179], v[60:63]
	v_mfma_f32_16x16x32_bf16 v[56:59], v[152:155], v[176:179], v[56:59]
	v_mfma_f32_16x16x32_bf16 v[44:47], v[144:147], v[184:187], v[44:47]
	v_mfma_f32_16x16x32_bf16 v[40:43], v[152:155], v[184:187], v[40:43]
	v_mfma_f32_16x16x32_bf16 v[28:31], v[144:147], v[216:219], v[28:31]
	v_mfma_f32_16x16x32_bf16 v[24:27], v[152:155], v[216:219], v[24:27]
	v_mfma_f32_16x16x32_bf16 v[12:15], v[144:147], v[224:227], v[12:15]
	v_mfma_f32_16x16x32_bf16 v[8:11], v[152:155], v[224:227], v[8:11]
	v_mfma_f32_16x16x32_bf16 v[60:63], v[148:151], v[180:183], v[60:63]
	v_mfma_f32_16x16x32_bf16 v[56:59], v[156:159], v[180:183], v[56:59]
	v_mfma_f32_16x16x32_bf16 v[44:47], v[148:151], v[202:205], v[44:47]
	v_mfma_f32_16x16x32_bf16 v[40:43], v[156:159], v[202:205], v[40:43]
	v_mfma_f32_16x16x32_bf16 v[28:31], v[148:151], v[220:223], v[28:31]
	v_mfma_f32_16x16x32_bf16 v[24:27], v[156:159], v[220:223], v[24:27]
	v_mfma_f32_16x16x32_bf16 v[12:15], v[148:151], v[228:231], v[12:15]
	v_mfma_f32_16x16x32_bf16 v[8:11], v[156:159], v[228:231], v[8:11]
	s_setprio 0
	s_setprio 1
	v_mfma_f32_16x16x32_bf16 v[52:55], v[160:163], v[176:179], v[52:55]
	v_mfma_f32_16x16x32_bf16 v[48:51], v[168:171], v[176:179], v[48:51]
	v_mfma_f32_16x16x32_bf16 v[36:39], v[160:163], v[184:187], v[36:39]
	v_mfma_f32_16x16x32_bf16 v[32:35], v[168:171], v[184:187], v[32:35]
	v_mfma_f32_16x16x32_bf16 v[20:23], v[160:163], v[216:219], v[20:23]
	v_mfma_f32_16x16x32_bf16 v[16:19], v[168:171], v[216:219], v[16:19]
	v_mfma_f32_16x16x32_bf16 v[4:7], v[160:163], v[224:227], v[4:7]
	v_mfma_f32_16x16x32_bf16 v[0:3], v[168:171], v[224:227], v[0:3]
	v_mfma_f32_16x16x32_bf16 v[52:55], v[164:167], v[180:183], v[52:55]
	v_mfma_f32_16x16x32_bf16 v[48:51], v[172:175], v[180:183], v[48:51]
	v_mfma_f32_16x16x32_bf16 v[36:39], v[164:167], v[202:205], v[36:39]
	v_mfma_f32_16x16x32_bf16 v[32:35], v[172:175], v[202:205], v[32:35]
	v_mfma_f32_16x16x32_bf16 v[20:23], v[164:167], v[220:223], v[20:23]
	v_mfma_f32_16x16x32_bf16 v[16:19], v[172:175], v[220:223], v[16:19]
	v_mfma_f32_16x16x32_bf16 v[4:7], v[164:167], v[228:231], v[4:7]
	v_mfma_f32_16x16x32_bf16 v[0:3], v[172:175], v[228:231], v[0:3]
	s_setprio 0
	s_barrier
	s_setprio 2
	s_add_i32 s52, 0, 0x18000
	s_add_i32 s53, 0, 0x1c000
	v_add_u32_e32 v156, s52, v142
	v_add_u32_e32 v172, s53, v142
	ds_read_b128 v[144:147], v156
	ds_read_b128 v[148:151], v156 offset:1024
	ds_read_b128 v[152:155], v156 offset:2048
	ds_read_b128 v[156:159], v156 offset:3072
	ds_read_b128 v[160:163], v172
	ds_read_b128 v[164:167], v172 offset:1024
	ds_read_b128 v[168:171], v172 offset:2048
	ds_read_b128 v[172:175], v172 offset:3072
	s_add_u32 s20, s86, 0x40000
	s_addc_u32 s21, s87, 0
	s_mov_b32 m0, s46
	v_lshl_add_u64 v[236:237], s[20:21], 0, v[134:135]
	ds_read_b128 v[176:179], v143 offset:32768
	ds_read_b128 v[180:183], v143 offset:33792
	ds_read_b128 v[184:187], v143 offset:34816
	ds_read_b128 v[202:205], v143 offset:35840
	ds_read_b128 v[216:219], v143 offset:36864
	ds_read_b128 v[220:223], v143 offset:37888
	ds_read_b128 v[224:227], v143 offset:38912
	ds_read_b128 v[228:231], v143 offset:39936
	global_load_lds_dwordx4 v[236:237], off
	v_lshl_add_u64 v[236:237], s[20:21], 0, v[130:131]
	s_mov_b32 m0, s47
	s_nop 0
	global_load_lds_dwordx4 v[236:237], off
	s_waitcnt vmcnt(8)
	s_waitcnt lgkmcnt(0)
	s_barrier
	s_setprio 1
	s_waitcnt lgkmcnt(0)
	v_mfma_f32_16x16x32_bf16 v[124:127], v[144:147], v[176:179], v[124:127]
	v_mfma_f32_16x16x32_bf16 v[120:123], v[152:155], v[176:179], v[120:123]
	v_mfma_f32_16x16x32_bf16 v[108:111], v[144:147], v[184:187], v[108:111]
	v_mfma_f32_16x16x32_bf16 v[104:107], v[152:155], v[184:187], v[104:107]
	v_mfma_f32_16x16x32_bf16 v[92:95], v[144:147], v[216:219], v[92:95]
	v_mfma_f32_16x16x32_bf16 v[88:91], v[152:155], v[216:219], v[88:91]
	v_mfma_f32_16x16x32_bf16 v[76:79], v[144:147], v[224:227], v[76:79]
	v_mfma_f32_16x16x32_bf16 v[72:75], v[152:155], v[224:227], v[72:75]
	v_mfma_f32_16x16x32_bf16 v[124:127], v[148:151], v[180:183], v[124:127]
	v_mfma_f32_16x16x32_bf16 v[120:123], v[156:159], v[180:183], v[120:123]
	v_mfma_f32_16x16x32_bf16 v[108:111], v[148:151], v[202:205], v[108:111]
	v_mfma_f32_16x16x32_bf16 v[104:107], v[156:159], v[202:205], v[104:107]
	v_mfma_f32_16x16x32_bf16 v[92:95], v[148:151], v[220:223], v[92:95]
	v_mfma_f32_16x16x32_bf16 v[88:91], v[156:159], v[220:223], v[88:91]
	v_mfma_f32_16x16x32_bf16 v[76:79], v[148:151], v[228:231], v[76:79]
	v_mfma_f32_16x16x32_bf16 v[72:75], v[156:159], v[228:231], v[72:75]
	s_setprio 0
	s_setprio 1
	v_mfma_f32_16x16x32_bf16 v[116:119], v[160:163], v[176:179], v[116:119]
	v_mfma_f32_16x16x32_bf16 v[112:115], v[168:171], v[176:179], v[112:115]
	v_mfma_f32_16x16x32_bf16 v[100:103], v[160:163], v[184:187], v[100:103]
	v_mfma_f32_16x16x32_bf16 v[96:99], v[168:171], v[184:187], v[96:99]
	v_mfma_f32_16x16x32_bf16 v[84:87], v[160:163], v[216:219], v[84:87]
	v_mfma_f32_16x16x32_bf16 v[80:83], v[168:171], v[216:219], v[80:83]
	v_mfma_f32_16x16x32_bf16 v[68:71], v[160:163], v[224:227], v[68:71]
	v_mfma_f32_16x16x32_bf16 v[64:67], v[168:171], v[224:227], v[64:67]
	v_mfma_f32_16x16x32_bf16 v[116:119], v[164:167], v[180:183], v[116:119]
	v_mfma_f32_16x16x32_bf16 v[112:115], v[172:175], v[180:183], v[112:115]
	v_mfma_f32_16x16x32_bf16 v[100:103], v[164:167], v[202:205], v[100:103]
	v_mfma_f32_16x16x32_bf16 v[96:99], v[172:175], v[202:205], v[96:99]
	v_mfma_f32_16x16x32_bf16 v[84:87], v[164:167], v[220:223], v[84:87]
	v_mfma_f32_16x16x32_bf16 v[80:83], v[172:175], v[220:223], v[80:83]
	v_mfma_f32_16x16x32_bf16 v[68:71], v[164:167], v[228:231], v[68:71]
	v_mfma_f32_16x16x32_bf16 v[64:67], v[172:175], v[228:231], v[64:67]
	s_setprio 0
	s_barrier
	s_setprio 2
	s_add_i32 s20, s52, s12
	v_lshl_add_u64 v[194:195], v[194:195], 0, s[62:63]
	s_mov_b32 m0, s20
	ds_read_b128 v[176:179], v143 offset:49152
	ds_read_b128 v[180:183], v143 offset:50176
	ds_read_b128 v[184:187], v143 offset:51200
	ds_read_b128 v[202:205], v143 offset:52224
	ds_read_b128 v[216:219], v143 offset:53248
	ds_read_b128 v[220:223], v143 offset:54272
	ds_read_b128 v[224:227], v143 offset:55296
	ds_read_b128 v[228:231], v143 offset:56320
	global_load_lds_dwordx4 v[194:195], off
	s_add_i32 m0, s20, 0x2000
	s_add_u32 s20, s82, 0x40080
	v_lshl_add_u64 v[194:195], v[196:197], 0, s[62:63]
	s_addc_u32 s21, s83, 0
	s_add_i32 s52, s53, s12
	global_load_lds_dwordx4 v[194:195], off
	v_lshl_add_u64 v[194:195], s[20:21], 0, v[132:133]
	s_mov_b32 m0, s52
	s_nop 0
	global_load_lds_dwordx4 v[194:195], off
	v_lshl_add_u64 v[194:195], s[20:21], 0, v[128:129]
	s_add_i32 m0, s52, 0x2000
	s_nop 0
	global_load_lds_dwordx4 v[194:195], off
	v_lshl_add_u64 v[194:195], v[232:233], 0, s[62:63]
	s_mov_b32 m0, s56
	s_nop 0
	global_load_lds_dwordx4 v[194:195], off
	v_lshl_add_u64 v[194:195], v[234:235], 0, s[62:63]
	s_mov_b32 m0, s57
	s_nop 0
	global_load_lds_dwordx4 v[194:195], off
	s_waitcnt vmcnt(8)
	s_waitcnt lgkmcnt(0)
	s_barrier
	s_setprio 1
	s_waitcnt lgkmcnt(0)
	v_mfma_f32_16x16x32_bf16 v[60:63], v[144:147], v[176:179], v[60:63]
	v_mfma_f32_16x16x32_bf16 v[56:59], v[152:155], v[176:179], v[56:59]
	v_mfma_f32_16x16x32_bf16 v[44:47], v[144:147], v[184:187], v[44:47]
	v_mfma_f32_16x16x32_bf16 v[40:43], v[152:155], v[184:187], v[40:43]
	v_mfma_f32_16x16x32_bf16 v[28:31], v[144:147], v[216:219], v[28:31]
	v_mfma_f32_16x16x32_bf16 v[24:27], v[152:155], v[216:219], v[24:27]
	v_mfma_f32_16x16x32_bf16 v[12:15], v[144:147], v[224:227], v[12:15]
	v_mfma_f32_16x16x32_bf16 v[8:11], v[152:155], v[224:227], v[8:11]
	v_mfma_f32_16x16x32_bf16 v[60:63], v[148:151], v[180:183], v[60:63]
	v_mfma_f32_16x16x32_bf16 v[56:59], v[156:159], v[180:183], v[56:59]
	v_mfma_f32_16x16x32_bf16 v[44:47], v[148:151], v[202:205], v[44:47]
	v_mfma_f32_16x16x32_bf16 v[40:43], v[156:159], v[202:205], v[40:43]
	v_mfma_f32_16x16x32_bf16 v[28:31], v[148:151], v[220:223], v[28:31]
	v_mfma_f32_16x16x32_bf16 v[24:27], v[156:159], v[220:223], v[24:27]
	v_mfma_f32_16x16x32_bf16 v[12:15], v[148:151], v[228:231], v[12:15]
	v_mfma_f32_16x16x32_bf16 v[8:11], v[156:159], v[228:231], v[8:11]
	s_setprio 0
	s_setprio 1
	v_mfma_f32_16x16x32_bf16 v[52:55], v[160:163], v[176:179], v[52:55]
	v_mfma_f32_16x16x32_bf16 v[48:51], v[168:171], v[176:179], v[48:51]
	v_mfma_f32_16x16x32_bf16 v[36:39], v[160:163], v[184:187], v[36:39]
	v_mfma_f32_16x16x32_bf16 v[32:35], v[168:171], v[184:187], v[32:35]
	v_mfma_f32_16x16x32_bf16 v[20:23], v[160:163], v[216:219], v[20:23]
	v_mfma_f32_16x16x32_bf16 v[16:19], v[168:171], v[216:219], v[16:19]
	v_mfma_f32_16x16x32_bf16 v[4:7], v[160:163], v[224:227], v[4:7]
	v_mfma_f32_16x16x32_bf16 v[0:3], v[168:171], v[224:227], v[0:3]
	v_mfma_f32_16x16x32_bf16 v[52:55], v[164:167], v[180:183], v[52:55]
	v_mfma_f32_16x16x32_bf16 v[48:51], v[172:175], v[180:183], v[48:51]
	v_mfma_f32_16x16x32_bf16 v[36:39], v[164:167], v[202:205], v[36:39]
	v_mfma_f32_16x16x32_bf16 v[32:35], v[172:175], v[202:205], v[32:35]
	v_mfma_f32_16x16x32_bf16 v[20:23], v[164:167], v[220:223], v[20:23]
	v_mfma_f32_16x16x32_bf16 v[16:19], v[172:175], v[220:223], v[16:19]
	v_mfma_f32_16x16x32_bf16 v[4:7], v[164:167], v[228:231], v[4:7]
	v_mfma_f32_16x16x32_bf16 v[0:3], v[172:175], v[228:231], v[0:3]
	s_setprio 0
	s_barrier
	s_setprio 2
	s_add_u32 s66, s66, 0x100
	s_addc_u32 s67, s67, 0
	s_add_u32 s94, s94, 0x100
	s_addc_u32 s95, s95, 0
	s_cmp_ge_i32 vcc_lo, s48
	s_mov_b32 s82, vcc_lo
	s_cbranch_scc0 .LBB0_316
	s_setprio 0
	s_mov_b64 s[88:89], 0x8000

.LBB0_578:
	s_add_i32 s95, s42, 2
	s_add_u32 s43, s40, 0xfffc0080
	s_addc_u32 s56, s41, -1
	s_add_i32 vcc_lo, 0, 0x10000
	s_cmp_eq_u32 s87, s42
	s_cselect_b32 s57, s49, s56
	s_cselect_b32 s56, s51, s43
	s_cselect_b32 s43, s59, s94
	s_cselect_b32 s42, s88, s89
	s_add_i32 s36, 0, 0x14000
	v_add_u32_e32 v150, vcc_lo, v156
	v_add_u32_e32 v170, s36, v156
	ds_read_b128 v[128:131], v150
	ds_read_b128 v[132:135], v150 offset:1024
	ds_read_b128 v[146:149], v150 offset:2048
	ds_read_b128 v[150:153], v150 offset:3072
	ds_read_b128 v[158:161], v170
	ds_read_b128 v[162:165], v170 offset:1024
	ds_read_b128 v[166:169], v170 offset:2048
	ds_read_b128 v[170:173], v170 offset:3072
	v_lshl_add_u64 v[186:187], s[40:41], 0, v[142:143]
	s_add_i32 m0, s5, 0xc000
	ds_read_b128 v[174:177], v157
	ds_read_b128 v[178:181], v157 offset:1024
	ds_read_b128 v[182:185], v157 offset:2048
	ds_read_b128 v[194:197], v157 offset:3072
	ds_read_b128 v[202:205], v157 offset:4096
	ds_read_b128 v[216:219], v157 offset:5120
	ds_read_b128 v[220:223], v157 offset:6144
	ds_read_b128 v[224:227], v157 offset:7168
	global_load_lds_dwordx4 v[186:187], off
	v_lshl_add_u64 v[186:187], s[40:41], 0, v[144:145]
	s_add_i32 m0, s5, 0xe000
	s_nop 0
	global_load_lds_dwordx4 v[186:187], off
	s_waitcnt vmcnt(8)
	s_waitcnt lgkmcnt(0)
	s_barrier
	s_setprio 1
	s_waitcnt lgkmcnt(0)
	v_mfma_f32_16x16x32_bf16 v[124:127], v[128:131], v[174:177], v[124:127]
	v_mfma_f32_16x16x32_bf16 v[120:123], v[146:149], v[174:177], v[120:123]
	v_mfma_f32_16x16x32_bf16 v[108:111], v[128:131], v[182:185], v[108:111]
	v_mfma_f32_16x16x32_bf16 v[104:107], v[146:149], v[182:185], v[104:107]
	v_mfma_f32_16x16x32_bf16 v[92:95], v[128:131], v[202:205], v[92:95]
	v_mfma_f32_16x16x32_bf16 v[88:91], v[146:149], v[202:205], v[88:91]
	v_mfma_f32_16x16x32_bf16 v[76:79], v[128:131], v[220:223], v[76:79]
	v_mfma_f32_16x16x32_bf16 v[72:75], v[146:149], v[220:223], v[72:75]
	v_mfma_f32_16x16x32_bf16 v[124:127], v[132:135], v[178:181], v[124:127]
	v_mfma_f32_16x16x32_bf16 v[120:123], v[150:153], v[178:181], v[120:123]
	v_mfma_f32_16x16x32_bf16 v[108:111], v[132:135], v[194:197], v[108:111]
	v_mfma_f32_16x16x32_bf16 v[104:107], v[150:153], v[194:197], v[104:107]
	v_mfma_f32_16x16x32_bf16 v[92:95], v[132:135], v[216:219], v[92:95]
	v_mfma_f32_16x16x32_bf16 v[88:91], v[150:153], v[216:219], v[88:91]
	v_mfma_f32_16x16x32_bf16 v[76:79], v[132:135], v[224:227], v[76:79]
	v_mfma_f32_16x16x32_bf16 v[72:75], v[150:153], v[224:227], v[72:75]
	s_setprio 0
	s_setprio 1
	v_mfma_f32_16x16x32_bf16 v[116:119], v[158:161], v[174:177], v[116:119]
	v_mfma_f32_16x16x32_bf16 v[112:115], v[166:169], v[174:177], v[112:115]
	v_mfma_f32_16x16x32_bf16 v[100:103], v[158:161], v[182:185], v[100:103]
	v_mfma_f32_16x16x32_bf16 v[96:99], v[166:169], v[182:185], v[96:99]
	v_mfma_f32_16x16x32_bf16 v[84:87], v[158:161], v[202:205], v[84:87]
	v_mfma_f32_16x16x32_bf16 v[80:83], v[166:169], v[202:205], v[80:83]
	v_mfma_f32_16x16x32_bf16 v[68:71], v[158:161], v[220:223], v[68:71]
	v_mfma_f32_16x16x32_bf16 v[64:67], v[166:169], v[220:223], v[64:67]
	v_mfma_f32_16x16x32_bf16 v[116:119], v[162:165], v[178:181], v[116:119]
	v_mfma_f32_16x16x32_bf16 v[112:115], v[170:173], v[178:181], v[112:115]
	v_mfma_f32_16x16x32_bf16 v[100:103], v[162:165], v[194:197], v[100:103]
	v_mfma_f32_16x16x32_bf16 v[96:99], v[170:173], v[194:197], v[96:99]
	v_mfma_f32_16x16x32_bf16 v[84:87], v[162:165], v[216:219], v[84:87]
	v_mfma_f32_16x16x32_bf16 v[80:83], v[170:173], v[216:219], v[80:83]
	v_mfma_f32_16x16x32_bf16 v[68:71], v[162:165], v[224:227], v[68:71]
	v_mfma_f32_16x16x32_bf16 v[64:67], v[170:173], v[224:227], v[64:67]
	s_setprio 0
	s_barrier
	s_setprio 2
	s_add_i32 s37, vcc_lo, s60
	v_lshl_add_u64 v[186:187], s[42:43], 0, v[188:189]
	s_mov_b32 m0, s37
	ds_read_b128 v[174:177], v157 offset:16384
	ds_read_b128 v[178:181], v157 offset:17408
	ds_read_b128 v[182:185], v157 offset:18432
	ds_read_b128 v[194:197], v157 offset:19456
	ds_read_b128 v[202:205], v157 offset:20480
	ds_read_b128 v[216:219], v157 offset:21504
	ds_read_b128 v[220:223], v157 offset:22528
	ds_read_b128 v[224:227], v157 offset:23552
	global_load_lds_dwordx4 v[186:187], off
	s_add_i32 m0, s37, 0x2000
	s_add_u32 vcc_lo, s42, 0x40000
	v_lshl_add_u64 v[228:229], s[42:43], 0, v[136:137]
	s_addc_u32 vcc_hi, s43, 0
	s_add_i32 s36, s36, s60
	global_load_lds_dwordx4 v[228:229], off
	v_lshl_add_u64 v[230:231], vcc, 0, v[188:189]
	s_mov_b32 m0, s36
	v_lshl_add_u64 v[232:233], s[56:57], 0, v[138:139]
	global_load_lds_dwordx4 v[230:231], off
	v_lshl_add_u64 v[230:231], vcc, 0, v[136:137]
	s_add_i32 m0, s36, 0x2000
	s_nop 0
	global_load_lds_dwordx4 v[230:231], off
	v_lshl_add_u64 v[230:231], s[56:57], 0, v[140:141]
	s_mov_b32 m0, s5
	s_nop 0
	global_load_lds_dwordx4 v[230:231], off
	s_mov_b32 m0, s6
	s_nop 0
	global_load_lds_dwordx4 v[232:233], off
	s_waitcnt vmcnt(8)
	s_waitcnt lgkmcnt(0)
	s_barrier
	s_setprio 1
	s_waitcnt lgkmcnt(0)
	v_mfma_f32_16x16x32_bf16 v[60:63], v[128:131], v[174:177], v[60:63]
	v_mfma_f32_16x16x32_bf16 v[56:59], v[146:149], v[174:177], v[56:59]
	v_mfma_f32_16x16x32_bf16 v[44:47], v[128:131], v[182:185], v[44:47]
	v_mfma_f32_16x16x32_bf16 v[40:43], v[146:149], v[182:185], v[40:43]
	v_mfma_f32_16x16x32_bf16 v[28:31], v[128:131], v[202:205], v[28:31]
	v_mfma_f32_16x16x32_bf16 v[24:27], v[146:149], v[202:205], v[24:27]
	v_mfma_f32_16x16x32_bf16 v[12:15], v[128:131], v[220:223], v[12:15]
	v_mfma_f32_16x16x32_bf16 v[8:11], v[146:149], v[220:223], v[8:11]
	v_mfma_f32_16x16x32_bf16 v[60:63], v[132:135], v[178:181], v[60:63]
	v_mfma_f32_16x16x32_bf16 v[56:59], v[150:153], v[178:181], v[56:59]
	v_mfma_f32_16x16x32_bf16 v[44:47], v[132:135], v[194:197], v[44:47]
	v_mfma_f32_16x16x32_bf16 v[40:43], v[150:153], v[194:197], v[40:43]
	v_mfma_f32_16x16x32_bf16 v[28:31], v[132:135], v[216:219], v[28:31]
	v_mfma_f32_16x16x32_bf16 v[24:27], v[150:153], v[216:219], v[24:27]
	v_mfma_f32_16x16x32_bf16 v[12:15], v[132:135], v[224:227], v[12:15]
	v_mfma_f32_16x16x32_bf16 v[8:11], v[150:153], v[224:227], v[8:11]
	s_setprio 0
	s_setprio 1
	v_mfma_f32_16x16x32_bf16 v[52:55], v[158:161], v[174:177], v[52:55]
	v_mfma_f32_16x16x32_bf16 v[48:51], v[166:169], v[174:177], v[48:51]
	v_mfma_f32_16x16x32_bf16 v[36:39], v[158:161], v[182:185], v[36:39]
	v_mfma_f32_16x16x32_bf16 v[32:35], v[166:169], v[182:185], v[32:35]
	v_mfma_f32_16x16x32_bf16 v[20:23], v[158:161], v[202:205], v[20:23]
	v_mfma_f32_16x16x32_bf16 v[16:19], v[166:169], v[202:205], v[16:19]
	v_mfma_f32_16x16x32_bf16 v[4:7], v[158:161], v[220:223], v[4:7]
	v_mfma_f32_16x16x32_bf16 v[0:3], v[166:169], v[220:223], v[0:3]
	v_mfma_f32_16x16x32_bf16 v[52:55], v[162:165], v[178:181], v[52:55]
	v_mfma_f32_16x16x32_bf16 v[48:51], v[170:173], v[178:181], v[48:51]
	v_mfma_f32_16x16x32_bf16 v[36:39], v[162:165], v[194:197], v[36:39]
	v_mfma_f32_16x16x32_bf16 v[32:35], v[170:173], v[194:197], v[32:35]
	v_mfma_f32_16x16x32_bf16 v[20:23], v[162:165], v[216:219], v[20:23]
	v_mfma_f32_16x16x32_bf16 v[16:19], v[170:173], v[216:219], v[16:19]
	v_mfma_f32_16x16x32_bf16 v[4:7], v[162:165], v[224:227], v[4:7]
	v_mfma_f32_16x16x32_bf16 v[0:3], v[170:173], v[224:227], v[0:3]
	s_setprio 0
	s_barrier
	s_setprio 2
	s_add_i32 s36, 0, 0x18000
	s_add_i32 s37, 0, 0x1c000
	v_add_u32_e32 v150, s36, v156
	v_add_u32_e32 v170, s37, v156
	ds_read_b128 v[128:131], v150
	ds_read_b128 v[132:135], v150 offset:1024
	ds_read_b128 v[146:149], v150 offset:2048
	ds_read_b128 v[150:153], v150 offset:3072
	ds_read_b128 v[158:161], v170
	ds_read_b128 v[162:165], v170 offset:1024
	ds_read_b128 v[166:169], v170 offset:2048
	ds_read_b128 v[170:173], v170 offset:3072
	s_add_u32 s56, s56, 0x40000
	s_addc_u32 s57, s57, 0
	s_mov_b32 m0, s7
	v_lshl_add_u64 v[234:235], s[56:57], 0, v[140:141]
	ds_read_b128 v[174:177], v157 offset:32768
	ds_read_b128 v[178:181], v157 offset:33792
	ds_read_b128 v[182:185], v157 offset:34816
	ds_read_b128 v[194:197], v157 offset:35840
	ds_read_b128 v[202:205], v157 offset:36864
	ds_read_b128 v[216:219], v157 offset:37888
	ds_read_b128 v[220:223], v157 offset:38912
	ds_read_b128 v[224:227], v157 offset:39936
	global_load_lds_dwordx4 v[234:235], off
	v_lshl_add_u64 v[234:235], s[56:57], 0, v[138:139]
	s_mov_b32 m0, s8
	s_nop 0
	global_load_lds_dwordx4 v[234:235], off
	s_waitcnt vmcnt(8)
	s_waitcnt lgkmcnt(0)
	s_barrier
	s_setprio 1
	s_waitcnt lgkmcnt(0)
	v_mfma_f32_16x16x32_bf16 v[124:127], v[128:131], v[174:177], v[124:127]
	v_mfma_f32_16x16x32_bf16 v[120:123], v[146:149], v[174:177], v[120:123]
	v_mfma_f32_16x16x32_bf16 v[108:111], v[128:131], v[182:185], v[108:111]
	v_mfma_f32_16x16x32_bf16 v[104:107], v[146:149], v[182:185], v[104:107]
	v_mfma_f32_16x16x32_bf16 v[92:95], v[128:131], v[202:205], v[92:95]
	v_mfma_f32_16x16x32_bf16 v[88:91], v[146:149], v[202:205], v[88:91]
	v_mfma_f32_16x16x32_bf16 v[76:79], v[128:131], v[220:223], v[76:79]
	v_mfma_f32_16x16x32_bf16 v[72:75], v[146:149], v[220:223], v[72:75]
	v_mfma_f32_16x16x32_bf16 v[124:127], v[132:135], v[178:181], v[124:127]
	v_mfma_f32_16x16x32_bf16 v[120:123], v[150:153], v[178:181], v[120:123]
	v_mfma_f32_16x16x32_bf16 v[108:111], v[132:135], v[194:197], v[108:111]
	v_mfma_f32_16x16x32_bf16 v[104:107], v[150:153], v[194:197], v[104:107]
	v_mfma_f32_16x16x32_bf16 v[92:95], v[132:135], v[216:219], v[92:95]
	v_mfma_f32_16x16x32_bf16 v[88:91], v[150:153], v[216:219], v[88:91]
	v_mfma_f32_16x16x32_bf16 v[76:79], v[132:135], v[224:227], v[76:79]
	v_mfma_f32_16x16x32_bf16 v[72:75], v[150:153], v[224:227], v[72:75]
	s_setprio 0
	s_setprio 1
	v_mfma_f32_16x16x32_bf16 v[116:119], v[158:161], v[174:177], v[116:119]
	v_mfma_f32_16x16x32_bf16 v[112:115], v[166:169], v[174:177], v[112:115]
	v_mfma_f32_16x16x32_bf16 v[100:103], v[158:161], v[182:185], v[100:103]
	v_mfma_f32_16x16x32_bf16 v[96:99], v[166:169], v[182:185], v[96:99]
	v_mfma_f32_16x16x32_bf16 v[84:87], v[158:161], v[202:205], v[84:87]
	v_mfma_f32_16x16x32_bf16 v[80:83], v[166:169], v[202:205], v[80:83]
	v_mfma_f32_16x16x32_bf16 v[68:71], v[158:161], v[220:223], v[68:71]
	v_mfma_f32_16x16x32_bf16 v[64:67], v[166:169], v[220:223], v[64:67]
	v_mfma_f32_16x16x32_bf16 v[116:119], v[162:165], v[178:181], v[116:119]
	v_mfma_f32_16x16x32_bf16 v[112:115], v[170:173], v[178:181], v[112:115]
	v_mfma_f32_16x16x32_bf16 v[100:103], v[162:165], v[194:197], v[100:103]
	v_mfma_f32_16x16x32_bf16 v[96:99], v[170:173], v[194:197], v[96:99]
	v_mfma_f32_16x16x32_bf16 v[84:87], v[162:165], v[216:219], v[84:87]
	v_mfma_f32_16x16x32_bf16 v[80:83], v[170:173], v[216:219], v[80:83]
	v_mfma_f32_16x16x32_bf16 v[68:71], v[162:165], v[224:227], v[68:71]
	v_mfma_f32_16x16x32_bf16 v[64:67], v[170:173], v[224:227], v[64:67]
	s_setprio 0
	s_barrier
	s_setprio 2
	s_add_i32 s36, s36, s60
	v_lshl_add_u64 v[186:187], v[186:187], 0, s[62:63]
	s_mov_b32 m0, s36
	ds_read_b128 v[174:177], v157 offset:49152
	ds_read_b128 v[178:181], v157 offset:50176
	ds_read_b128 v[182:185], v157 offset:51200
	ds_read_b128 v[194:197], v157 offset:52224
	ds_read_b128 v[202:205], v157 offset:53248
	ds_read_b128 v[216:219], v157 offset:54272
	ds_read_b128 v[220:223], v157 offset:55296
	ds_read_b128 v[224:227], v157 offset:56320
	global_load_lds_dwordx4 v[186:187], off
	s_add_i32 m0, s36, 0x2000
	s_add_u32 s42, s42, 0x40080
	v_lshl_add_u64 v[186:187], v[228:229], 0, s[62:63]
	s_addc_u32 s43, s43, 0
	s_add_i32 s36, s37, s60
	global_load_lds_dwordx4 v[186:187], off
	v_lshl_add_u64 v[186:187], s[42:43], 0, v[188:189]
	s_mov_b32 m0, s36
	s_nop 0
	global_load_lds_dwordx4 v[186:187], off
	v_lshl_add_u64 v[186:187], s[42:43], 0, v[136:137]
	s_add_i32 m0, s36, 0x2000
	s_nop 0
	global_load_lds_dwordx4 v[186:187], off
	v_lshl_add_u64 v[186:187], v[230:231], 0, s[62:63]
	s_mov_b32 m0, s85
	s_nop 0
	global_load_lds_dwordx4 v[186:187], off
	v_lshl_add_u64 v[186:187], v[232:233], 0, s[62:63]
	s_mov_b32 m0, s86
	s_nop 0
	global_load_lds_dwordx4 v[186:187], off
	s_waitcnt vmcnt(8)
	s_waitcnt lgkmcnt(0)
	s_barrier
	s_setprio 1
	s_waitcnt lgkmcnt(0)
	v_mfma_f32_16x16x32_bf16 v[60:63], v[128:131], v[174:177], v[60:63]
	v_mfma_f32_16x16x32_bf16 v[56:59], v[146:149], v[174:177], v[56:59]
	v_mfma_f32_16x16x32_bf16 v[44:47], v[128:131], v[182:185], v[44:47]
	v_mfma_f32_16x16x32_bf16 v[40:43], v[146:149], v[182:185], v[40:43]
	v_mfma_f32_16x16x32_bf16 v[28:31], v[128:131], v[202:205], v[28:31]
	v_mfma_f32_16x16x32_bf16 v[24:27], v[146:149], v[202:205], v[24:27]
	v_mfma_f32_16x16x32_bf16 v[12:15], v[128:131], v[220:223], v[12:15]
	v_mfma_f32_16x16x32_bf16 v[8:11], v[146:149], v[220:223], v[8:11]
	v_mfma_f32_16x16x32_bf16 v[60:63], v[132:135], v[178:181], v[60:63]
	v_mfma_f32_16x16x32_bf16 v[56:59], v[150:153], v[178:181], v[56:59]
	v_mfma_f32_16x16x32_bf16 v[44:47], v[132:135], v[194:197], v[44:47]
	v_mfma_f32_16x16x32_bf16 v[40:43], v[150:153], v[194:197], v[40:43]
	v_mfma_f32_16x16x32_bf16 v[28:31], v[132:135], v[216:219], v[28:31]
	v_mfma_f32_16x16x32_bf16 v[24:27], v[150:153], v[216:219], v[24:27]
	v_mfma_f32_16x16x32_bf16 v[12:15], v[132:135], v[224:227], v[12:15]
	v_mfma_f32_16x16x32_bf16 v[8:11], v[150:153], v[224:227], v[8:11]
	s_setprio 0
	s_setprio 1
	v_mfma_f32_16x16x32_bf16 v[52:55], v[158:161], v[174:177], v[52:55]
	v_mfma_f32_16x16x32_bf16 v[48:51], v[166:169], v[174:177], v[48:51]
	v_mfma_f32_16x16x32_bf16 v[36:39], v[158:161], v[182:185], v[36:39]
	v_mfma_f32_16x16x32_bf16 v[32:35], v[166:169], v[182:185], v[32:35]
	v_mfma_f32_16x16x32_bf16 v[20:23], v[158:161], v[202:205], v[20:23]
	v_mfma_f32_16x16x32_bf16 v[16:19], v[166:169], v[202:205], v[16:19]
	v_mfma_f32_16x16x32_bf16 v[4:7], v[158:161], v[220:223], v[4:7]
	v_mfma_f32_16x16x32_bf16 v[0:3], v[166:169], v[220:223], v[0:3]
	v_mfma_f32_16x16x32_bf16 v[52:55], v[162:165], v[178:181], v[52:55]
	v_mfma_f32_16x16x32_bf16 v[48:51], v[170:173], v[178:181], v[48:51]
	v_mfma_f32_16x16x32_bf16 v[36:39], v[162:165], v[194:197], v[36:39]
	v_mfma_f32_16x16x32_bf16 v[32:35], v[170:173], v[194:197], v[32:35]
	v_mfma_f32_16x16x32_bf16 v[20:23], v[162:165], v[216:219], v[20:23]
	v_mfma_f32_16x16x32_bf16 v[16:19], v[170:173], v[216:219], v[16:19]
	v_mfma_f32_16x16x32_bf16 v[4:7], v[162:165], v[224:227], v[4:7]
	v_mfma_f32_16x16x32_bf16 v[0:3], v[170:173], v[224:227], v[0:3]
	s_setprio 0
	s_barrier
	s_setprio 2
	s_add_u32 s40, s40, 0x100
	s_addc_u32 s41, s41, 0
	s_add_u32 s89, s89, 0x100
	s_addc_u32 s94, s94, 0
	s_cmp_ge_i32 s95, s81
	s_mov_b32 s42, s95
	s_cbranch_scc0 .LBB0_578
	s_setprio 0

.LBB0_734:
	s_add_i32 s85, s48, 2
	s_add_u32 s49, s38, 0xfffc0080
	s_addc_u32 s50, s39, -1
	s_add_i32 s86, 0, 0x10000
	s_cmp_eq_u32 s70, s48
	s_cselect_b32 s51, s41, s50
	s_cselect_b32 s50, s43, s49
	v_add_u32_e32 v146, s86, v150
	s_cselect_b32 s49, s81, s84
	s_cselect_b32 s48, s82, s83
	s_add_i32 s88, 0, 0x14000
	ds_read_b128 v[138:141], v146
	ds_read_b128 v[142:145], v146 offset:1024
	ds_read_b128 v[152:155], v146 offset:2048
	ds_read_b128 v[156:159], v146 offset:3072
	v_add_u32_e32 v146, s88, v150
	ds_read_b128 v[160:163], v146
	ds_read_b128 v[164:167], v146 offset:1024
	ds_read_b128 v[168:171], v146 offset:2048
	ds_read_b128 v[172:175], v146 offset:3072
	v_lshl_add_u64 v[146:147], s[38:39], 0, v[134:135]
	s_add_i32 m0, s55, 0xc000
	ds_read_b128 v[176:179], v151
	ds_read_b128 v[180:183], v151 offset:1024
	ds_read_b128 v[184:187], v151 offset:2048
	ds_read_b128 v[194:197], v151 offset:3072
	ds_read_b128 v[202:205], v151 offset:4096
	ds_read_b128 v[216:219], v151 offset:5120
	ds_read_b128 v[220:223], v151 offset:6144
	ds_read_b128 v[224:227], v151 offset:7168
	global_load_lds_dwordx4 v[146:147], off
	v_lshl_add_u64 v[146:147], s[38:39], 0, v[136:137]
	s_add_i32 m0, s55, 0xe000
	s_nop 0
	global_load_lds_dwordx4 v[146:147], off
	s_waitcnt vmcnt(8)
	s_waitcnt lgkmcnt(0)
	s_barrier
	s_setprio 1
	s_waitcnt lgkmcnt(0)
	v_mfma_f32_16x16x32_bf16 v[124:127], v[138:141], v[176:179], v[124:127]
	v_mfma_f32_16x16x32_bf16 v[120:123], v[152:155], v[176:179], v[120:123]
	v_mfma_f32_16x16x32_bf16 v[108:111], v[138:141], v[184:187], v[108:111]
	v_mfma_f32_16x16x32_bf16 v[104:107], v[152:155], v[184:187], v[104:107]
	v_mfma_f32_16x16x32_bf16 v[92:95], v[138:141], v[202:205], v[92:95]
	v_mfma_f32_16x16x32_bf16 v[88:91], v[152:155], v[202:205], v[88:91]
	v_mfma_f32_16x16x32_bf16 v[76:79], v[138:141], v[220:223], v[76:79]
	v_mfma_f32_16x16x32_bf16 v[72:75], v[152:155], v[220:223], v[72:75]
	v_mfma_f32_16x16x32_bf16 v[124:127], v[142:145], v[180:183], v[124:127]
	v_mfma_f32_16x16x32_bf16 v[120:123], v[156:159], v[180:183], v[120:123]
	v_mfma_f32_16x16x32_bf16 v[108:111], v[142:145], v[194:197], v[108:111]
	v_mfma_f32_16x16x32_bf16 v[104:107], v[156:159], v[194:197], v[104:107]
	v_mfma_f32_16x16x32_bf16 v[92:95], v[142:145], v[216:219], v[92:95]
	v_mfma_f32_16x16x32_bf16 v[88:91], v[156:159], v[216:219], v[88:91]
	v_mfma_f32_16x16x32_bf16 v[76:79], v[142:145], v[224:227], v[76:79]
	v_mfma_f32_16x16x32_bf16 v[72:75], v[156:159], v[224:227], v[72:75]
	s_setprio 0
	s_setprio 1
	v_mfma_f32_16x16x32_bf16 v[116:119], v[160:163], v[176:179], v[116:119]
	v_mfma_f32_16x16x32_bf16 v[112:115], v[168:171], v[176:179], v[112:115]
	v_mfma_f32_16x16x32_bf16 v[100:103], v[160:163], v[184:187], v[100:103]
	v_mfma_f32_16x16x32_bf16 v[96:99], v[168:171], v[184:187], v[96:99]
	v_mfma_f32_16x16x32_bf16 v[84:87], v[160:163], v[202:205], v[84:87]
	v_mfma_f32_16x16x32_bf16 v[80:83], v[168:171], v[202:205], v[80:83]
	v_mfma_f32_16x16x32_bf16 v[68:71], v[160:163], v[220:223], v[68:71]
	v_mfma_f32_16x16x32_bf16 v[64:67], v[168:171], v[220:223], v[64:67]
	v_mfma_f32_16x16x32_bf16 v[116:119], v[164:167], v[180:183], v[116:119]
	v_mfma_f32_16x16x32_bf16 v[112:115], v[172:175], v[180:183], v[112:115]
	v_mfma_f32_16x16x32_bf16 v[100:103], v[164:167], v[194:197], v[100:103]
	v_mfma_f32_16x16x32_bf16 v[96:99], v[172:175], v[194:197], v[96:99]
	v_mfma_f32_16x16x32_bf16 v[84:87], v[164:167], v[216:219], v[84:87]
	v_mfma_f32_16x16x32_bf16 v[80:83], v[172:175], v[216:219], v[80:83]
	v_mfma_f32_16x16x32_bf16 v[68:71], v[164:167], v[224:227], v[68:71]
	v_mfma_f32_16x16x32_bf16 v[64:67], v[172:175], v[224:227], v[64:67]
	s_setprio 0
	s_barrier
	s_setprio 2
	s_add_i32 s86, s86, s54
	v_lshl_add_u64 v[146:147], s[48:49], 0, v[188:189]
	s_mov_b32 m0, s86
	ds_read_b128 v[176:179], v151 offset:16384
	ds_read_b128 v[180:183], v151 offset:17408
	ds_read_b128 v[184:187], v151 offset:18432
	ds_read_b128 v[194:197], v151 offset:19456
	ds_read_b128 v[202:205], v151 offset:20480
	ds_read_b128 v[216:219], v151 offset:21504
	ds_read_b128 v[220:223], v151 offset:22528
	ds_read_b128 v[224:227], v151 offset:23552
	global_load_lds_dwordx4 v[146:147], off
	s_add_i32 m0, s86, 0x2000
	s_add_u32 s86, s48, 0x40000
	v_lshl_add_u64 v[228:229], s[48:49], 0, v[128:129]
	s_addc_u32 s87, s49, 0
	s_add_i32 s88, s88, s54
	global_load_lds_dwordx4 v[228:229], off
	v_lshl_add_u64 v[230:231], s[86:87], 0, v[188:189]
	s_mov_b32 m0, s88
	v_lshl_add_u64 v[232:233], s[50:51], 0, v[130:131]
	global_load_lds_dwordx4 v[230:231], off
	v_lshl_add_u64 v[230:231], s[86:87], 0, v[128:129]
	s_add_i32 m0, s88, 0x2000
	s_nop 0
	global_load_lds_dwordx4 v[230:231], off
	v_lshl_add_u64 v[230:231], s[50:51], 0, v[132:133]
	s_mov_b32 m0, s55
	s_nop 0
	global_load_lds_dwordx4 v[230:231], off
	s_mov_b32 m0, s56
	s_nop 0
	global_load_lds_dwordx4 v[232:233], off
	s_waitcnt vmcnt(8)
	s_waitcnt lgkmcnt(0)
	s_barrier
	s_setprio 1
	s_waitcnt lgkmcnt(0)
	v_mfma_f32_16x16x32_bf16 v[60:63], v[138:141], v[176:179], v[60:63]
	v_mfma_f32_16x16x32_bf16 v[56:59], v[152:155], v[176:179], v[56:59]
	v_mfma_f32_16x16x32_bf16 v[44:47], v[138:141], v[184:187], v[44:47]
	v_mfma_f32_16x16x32_bf16 v[40:43], v[152:155], v[184:187], v[40:43]
	v_mfma_f32_16x16x32_bf16 v[28:31], v[138:141], v[202:205], v[28:31]
	v_mfma_f32_16x16x32_bf16 v[24:27], v[152:155], v[202:205], v[24:27]
	v_mfma_f32_16x16x32_bf16 v[12:15], v[138:141], v[220:223], v[12:15]
	v_mfma_f32_16x16x32_bf16 v[8:11], v[152:155], v[220:223], v[8:11]
	v_mfma_f32_16x16x32_bf16 v[60:63], v[142:145], v[180:183], v[60:63]
	v_mfma_f32_16x16x32_bf16 v[56:59], v[156:159], v[180:183], v[56:59]
	v_mfma_f32_16x16x32_bf16 v[44:47], v[142:145], v[194:197], v[44:47]
	v_mfma_f32_16x16x32_bf16 v[40:43], v[156:159], v[194:197], v[40:43]
	v_mfma_f32_16x16x32_bf16 v[28:31], v[142:145], v[216:219], v[28:31]
	v_mfma_f32_16x16x32_bf16 v[24:27], v[156:159], v[216:219], v[24:27]
	v_mfma_f32_16x16x32_bf16 v[12:15], v[142:145], v[224:227], v[12:15]
	v_mfma_f32_16x16x32_bf16 v[8:11], v[156:159], v[224:227], v[8:11]
	s_setprio 0
	s_setprio 1
	v_mfma_f32_16x16x32_bf16 v[52:55], v[160:163], v[176:179], v[52:55]
	v_mfma_f32_16x16x32_bf16 v[48:51], v[168:171], v[176:179], v[48:51]
	v_mfma_f32_16x16x32_bf16 v[36:39], v[160:163], v[184:187], v[36:39]
	v_mfma_f32_16x16x32_bf16 v[32:35], v[168:171], v[184:187], v[32:35]
	v_mfma_f32_16x16x32_bf16 v[20:23], v[160:163], v[202:205], v[20:23]
	v_mfma_f32_16x16x32_bf16 v[16:19], v[168:171], v[202:205], v[16:19]
	v_mfma_f32_16x16x32_bf16 v[4:7], v[160:163], v[220:223], v[4:7]
	v_mfma_f32_16x16x32_bf16 v[0:3], v[168:171], v[220:223], v[0:3]
	v_mfma_f32_16x16x32_bf16 v[52:55], v[164:167], v[180:183], v[52:55]
	v_mfma_f32_16x16x32_bf16 v[48:51], v[172:175], v[180:183], v[48:51]
	v_mfma_f32_16x16x32_bf16 v[36:39], v[164:167], v[194:197], v[36:39]
	v_mfma_f32_16x16x32_bf16 v[32:35], v[172:175], v[194:197], v[32:35]
	v_mfma_f32_16x16x32_bf16 v[20:23], v[164:167], v[216:219], v[20:23]
	v_mfma_f32_16x16x32_bf16 v[16:19], v[172:175], v[216:219], v[16:19]
	v_mfma_f32_16x16x32_bf16 v[4:7], v[164:167], v[224:227], v[4:7]
	v_mfma_f32_16x16x32_bf16 v[0:3], v[172:175], v[224:227], v[0:3]
	s_setprio 0
	s_barrier
	s_setprio 2
	s_add_i32 s86, 0, 0x18000
	s_add_i32 s87, 0, 0x1c000
	v_add_u32_e32 v156, s86, v150
	v_add_u32_e32 v172, s87, v150
	ds_read_b128 v[138:141], v156
	ds_read_b128 v[142:145], v156 offset:1024
	ds_read_b128 v[152:155], v156 offset:2048
	ds_read_b128 v[156:159], v156 offset:3072
	ds_read_b128 v[160:163], v172
	ds_read_b128 v[164:167], v172 offset:1024
	ds_read_b128 v[168:171], v172 offset:2048
	ds_read_b128 v[172:175], v172 offset:3072
	s_add_u32 s50, s50, 0x40000
	s_addc_u32 s51, s51, 0
	s_mov_b32 m0, s57
	v_lshl_add_u64 v[234:235], s[50:51], 0, v[132:133]
	ds_read_b128 v[176:179], v151 offset:32768
	ds_read_b128 v[180:183], v151 offset:33792
	ds_read_b128 v[184:187], v151 offset:34816
	ds_read_b128 v[194:197], v151 offset:35840
	ds_read_b128 v[202:205], v151 offset:36864
	ds_read_b128 v[216:219], v151 offset:37888
	ds_read_b128 v[220:223], v151 offset:38912
	ds_read_b128 v[224:227], v151 offset:39936
	global_load_lds_dwordx4 v[234:235], off
	v_lshl_add_u64 v[234:235], s[50:51], 0, v[130:131]
	s_mov_b32 m0, s58
	s_nop 0
	global_load_lds_dwordx4 v[234:235], off
	s_waitcnt vmcnt(8)
	s_waitcnt lgkmcnt(0)
	s_barrier
	s_setprio 1
	s_waitcnt lgkmcnt(0)
	v_mfma_f32_16x16x32_bf16 v[124:127], v[138:141], v[176:179], v[124:127]
	v_mfma_f32_16x16x32_bf16 v[120:123], v[152:155], v[176:179], v[120:123]
	v_mfma_f32_16x16x32_bf16 v[108:111], v[138:141], v[184:187], v[108:111]
	v_mfma_f32_16x16x32_bf16 v[104:107], v[152:155], v[184:187], v[104:107]
	v_mfma_f32_16x16x32_bf16 v[92:95], v[138:141], v[202:205], v[92:95]
	v_mfma_f32_16x16x32_bf16 v[88:91], v[152:155], v[202:205], v[88:91]
	v_mfma_f32_16x16x32_bf16 v[76:79], v[138:141], v[220:223], v[76:79]
	v_mfma_f32_16x16x32_bf16 v[72:75], v[152:155], v[220:223], v[72:75]
	v_mfma_f32_16x16x32_bf16 v[124:127], v[142:145], v[180:183], v[124:127]
	v_mfma_f32_16x16x32_bf16 v[120:123], v[156:159], v[180:183], v[120:123]
	v_mfma_f32_16x16x32_bf16 v[108:111], v[142:145], v[194:197], v[108:111]
	v_mfma_f32_16x16x32_bf16 v[104:107], v[156:159], v[194:197], v[104:107]
	v_mfma_f32_16x16x32_bf16 v[92:95], v[142:145], v[216:219], v[92:95]
	v_mfma_f32_16x16x32_bf16 v[88:91], v[156:159], v[216:219], v[88:91]
	v_mfma_f32_16x16x32_bf16 v[76:79], v[142:145], v[224:227], v[76:79]
	v_mfma_f32_16x16x32_bf16 v[72:75], v[156:159], v[224:227], v[72:75]
	s_setprio 0
	s_setprio 1
	v_mfma_f32_16x16x32_bf16 v[116:119], v[160:163], v[176:179], v[116:119]
	v_mfma_f32_16x16x32_bf16 v[112:115], v[168:171], v[176:179], v[112:115]
	v_mfma_f32_16x16x32_bf16 v[100:103], v[160:163], v[184:187], v[100:103]
	v_mfma_f32_16x16x32_bf16 v[96:99], v[168:171], v[184:187], v[96:99]
	v_mfma_f32_16x16x32_bf16 v[84:87], v[160:163], v[202:205], v[84:87]
	v_mfma_f32_16x16x32_bf16 v[80:83], v[168:171], v[202:205], v[80:83]
	v_mfma_f32_16x16x32_bf16 v[68:71], v[160:163], v[220:223], v[68:71]
	v_mfma_f32_16x16x32_bf16 v[64:67], v[168:171], v[220:223], v[64:67]
	v_mfma_f32_16x16x32_bf16 v[116:119], v[164:167], v[180:183], v[116:119]
	v_mfma_f32_16x16x32_bf16 v[112:115], v[172:175], v[180:183], v[112:115]
	v_mfma_f32_16x16x32_bf16 v[100:103], v[164:167], v[194:197], v[100:103]
	v_mfma_f32_16x16x32_bf16 v[96:99], v[172:175], v[194:197], v[96:99]
	v_mfma_f32_16x16x32_bf16 v[84:87], v[164:167], v[216:219], v[84:87]
	v_mfma_f32_16x16x32_bf16 v[80:83], v[172:175], v[216:219], v[80:83]
	v_mfma_f32_16x16x32_bf16 v[68:71], v[164:167], v[224:227], v[68:71]
	v_mfma_f32_16x16x32_bf16 v[64:67], v[172:175], v[224:227], v[64:67]
	s_setprio 0
	s_barrier
	s_setprio 2
	s_add_i32 s50, s86, s54
	v_lshl_add_u64 v[146:147], v[146:147], 0, s[62:63]
	s_mov_b32 m0, s50
	ds_read_b128 v[176:179], v151 offset:49152
	ds_read_b128 v[180:183], v151 offset:50176
	ds_read_b128 v[184:187], v151 offset:51200
	ds_read_b128 v[194:197], v151 offset:52224
	ds_read_b128 v[202:205], v151 offset:53248
	ds_read_b128 v[216:219], v151 offset:54272
	ds_read_b128 v[220:223], v151 offset:55296
	ds_read_b128 v[224:227], v151 offset:56320
	global_load_lds_dwordx4 v[146:147], off
	s_add_i32 m0, s50, 0x2000
	s_add_u32 s48, s48, 0x40080
	v_lshl_add_u64 v[146:147], v[228:229], 0, s[62:63]
	s_addc_u32 s49, s49, 0
	s_add_i32 s50, s87, s54
	global_load_lds_dwordx4 v[146:147], off
	v_lshl_add_u64 v[146:147], s[48:49], 0, v[188:189]
	s_mov_b32 m0, s50
	s_nop 0
	global_load_lds_dwordx4 v[146:147], off
	v_lshl_add_u64 v[146:147], s[48:49], 0, v[128:129]
	s_add_i32 m0, s50, 0x2000
	s_nop 0
	global_load_lds_dwordx4 v[146:147], off
	v_lshl_add_u64 v[146:147], v[230:231], 0, s[62:63]
	s_mov_b32 m0, s67
	s_nop 0
	global_load_lds_dwordx4 v[146:147], off
	v_lshl_add_u64 v[146:147], v[232:233], 0, s[62:63]
	s_mov_b32 m0, s69
	s_nop 0
	global_load_lds_dwordx4 v[146:147], off
	s_waitcnt vmcnt(8)
	s_waitcnt lgkmcnt(0)
	s_barrier
	s_setprio 1
	s_waitcnt lgkmcnt(0)
	v_mfma_f32_16x16x32_bf16 v[60:63], v[138:141], v[176:179], v[60:63]
	v_mfma_f32_16x16x32_bf16 v[56:59], v[152:155], v[176:179], v[56:59]
	v_mfma_f32_16x16x32_bf16 v[44:47], v[138:141], v[184:187], v[44:47]
	v_mfma_f32_16x16x32_bf16 v[40:43], v[152:155], v[184:187], v[40:43]
	v_mfma_f32_16x16x32_bf16 v[28:31], v[138:141], v[202:205], v[28:31]
	v_mfma_f32_16x16x32_bf16 v[24:27], v[152:155], v[202:205], v[24:27]
	v_mfma_f32_16x16x32_bf16 v[12:15], v[138:141], v[220:223], v[12:15]
	v_mfma_f32_16x16x32_bf16 v[8:11], v[152:155], v[220:223], v[8:11]
	v_mfma_f32_16x16x32_bf16 v[60:63], v[142:145], v[180:183], v[60:63]
	v_mfma_f32_16x16x32_bf16 v[56:59], v[156:159], v[180:183], v[56:59]
	v_mfma_f32_16x16x32_bf16 v[44:47], v[142:145], v[194:197], v[44:47]
	v_mfma_f32_16x16x32_bf16 v[40:43], v[156:159], v[194:197], v[40:43]
	v_mfma_f32_16x16x32_bf16 v[28:31], v[142:145], v[216:219], v[28:31]
	v_mfma_f32_16x16x32_bf16 v[24:27], v[156:159], v[216:219], v[24:27]
	v_mfma_f32_16x16x32_bf16 v[12:15], v[142:145], v[224:227], v[12:15]
	v_mfma_f32_16x16x32_bf16 v[8:11], v[156:159], v[224:227], v[8:11]
	s_setprio 0
	s_setprio 1
	v_mfma_f32_16x16x32_bf16 v[52:55], v[160:163], v[176:179], v[52:55]
	v_mfma_f32_16x16x32_bf16 v[48:51], v[168:171], v[176:179], v[48:51]
	v_mfma_f32_16x16x32_bf16 v[36:39], v[160:163], v[184:187], v[36:39]
	v_mfma_f32_16x16x32_bf16 v[32:35], v[168:171], v[184:187], v[32:35]
	v_mfma_f32_16x16x32_bf16 v[20:23], v[160:163], v[202:205], v[20:23]
	v_mfma_f32_16x16x32_bf16 v[16:19], v[168:171], v[202:205], v[16:19]
	v_mfma_f32_16x16x32_bf16 v[4:7], v[160:163], v[220:223], v[4:7]
	v_mfma_f32_16x16x32_bf16 v[0:3], v[168:171], v[220:223], v[0:3]
	v_mfma_f32_16x16x32_bf16 v[52:55], v[164:167], v[180:183], v[52:55]
	v_mfma_f32_16x16x32_bf16 v[48:51], v[172:175], v[180:183], v[48:51]
	v_mfma_f32_16x16x32_bf16 v[36:39], v[164:167], v[194:197], v[36:39]
	v_mfma_f32_16x16x32_bf16 v[32:35], v[172:175], v[194:197], v[32:35]
	v_mfma_f32_16x16x32_bf16 v[20:23], v[164:167], v[216:219], v[20:23]
	v_mfma_f32_16x16x32_bf16 v[16:19], v[172:175], v[216:219], v[16:19]
	v_mfma_f32_16x16x32_bf16 v[4:7], v[164:167], v[224:227], v[4:7]
	v_mfma_f32_16x16x32_bf16 v[0:3], v[172:175], v[224:227], v[0:3]
	s_setprio 0
	s_barrier
	s_setprio 2
	s_add_u32 s38, s38, 0x100
	s_addc_u32 s39, s39, 0
	s_add_u32 s83, s83, 0x100
	s_addc_u32 s84, s84, 0
	s_cmp_ge_i32 s85, s60
	s_mov_b32 s48, s85
	s_cbranch_scc0 .LBB0_734
	s_setprio 0
	s_mov_b64 s[88:89], 0x8000
